# v16 minus the redundant post-barrier lgkmcnt(0) at the head of each MFMA block (24 sites)
# speedup vs baseline: 1.0034x; 1.0034x over previous
; #define PG8_STAGE(bufoff, gbase, voff) do { _Pragma("unroll") for (int _i = 0; _i < 2; ++_i) \
;         __builtin_amdgcn_global_load_lds((const unsigned*)((const char*)(gbase) + (voff)[_i]), (PG8_LAS unsigned*)(lds + (bufoff) + ldsw + _i * 8192), 16, 0, 0); } while (0)
; #define PG8_LDA(dst, b, h) do { _Pragma("unroll") for (int m = 0; m < 4; ++m) _Pragma("unroll") for (int k = 0; k < 2; ++k) dst[m][k] = *(const PG8_LAS bf16x8*)(lds + PG8_SA(b, h) + aoff + m * 2048 + k * 1024); } while (0)
; #define PG8_LDB(dst, b, h) do { _Pragma("unroll") for (int n = 0; n < 2; ++n) _Pragma("unroll") for (int k = 0; k < 2; ++k) dst[n][k] = *(const PG8_LAS bf16x8*)(lds + PG8_SB(b, h) + boff + n * 2048 + k * 1024); } while (0)
; #define PG8_MMA(ai, bj, At, Bt) do { __builtin_amdgcn_s_setprio(1); _Pragma("unroll") for (int m = 0; m < 4; ++m) _Pragma("unroll") for (int n = 0; n < 2; ++n) _Pragma("unroll") for (int k = 0; k < 2; ++k) \
;         acc[ai][bj][m][n] = __builtin_amdgcn_mfma_f32_16x16x32_bf16(Bt[n][k], At[m][k], acc[ai][bj][m][n], 0, 0, 0); __builtin_amdgcn_s_setprio(0); } while (0)
; #define PG8_WAIT_V(n) asm volatile("s_waitcnt vmcnt(" #n ")" ::: "memory")
; #define PG8_WAIT_L(n) asm volatile("s_waitcnt lgkmcnt(" #n ")" ::: "memory")
; template <class Epi, class Sched, bool ALIGN_EPI = false, bool SP2 = false>
; __device__ __forceinline__ void gemm_phase(PG8_LAS unsigned char* lds, const Gemm g, const Sched& S, const Epi& E, const int tid_in) {
;     ...
;             const bool last = (t == nt - 2);
;             const char* a1 = cA + (size_t)(t + 1) * kstepA;
;             const char* a2 = last ? nA : cA + (size_t)(t + 2) * kstepA; const char* b2 = last ? nB : cB + (size_t)(t + 2) * kstepB;
;             const char* a3 = a2 + kstepA; const char* b3 = b2 + kstepB;
;             if (last && has_next) S.a_ready(nxt);
;             if constexpr (SP2) {
;             PG8_LDB(B0, 0, 0); PG8_LDB(B1, 0, 1); PG8_SCHED; PG8_LDA(At, 0, 0); PG8_STAGE(PG8_SA(1, 1), a1 + hstepA, voffA);
;             PG8_WAIT_V(8); PG8_WAIT_L(0); PG8_BAR; PG8_MMA(0, 0, At, B0); PG8_MMA(0, 1, At, B1); PG8_BAR; PG8_SCHED;
;             PG8_LDA(At, 0, 1); PG8_STAGE(PG8_SB(0, 0), b2, voffB); PG8_STAGE(PG8_SB(0, 1), b2 + hstepB, voffB); PG8_STAGE(PG8_SA(0, 0), a2, voffA);
;             PG8_WAIT_V(8); PG8_WAIT_L(0); PG8_BAR; PG8_MMA(1, 0, At, B0); PG8_MMA(1, 1, At, B1); PG8_BAR; PG8_SCHED;
.LBB0_118:
	s_andn2_b64 vcc, exec, s[18:19]
	s_cbranch_vccnz .Lzero_acc_1
	s_add_u32 s26, s26, 0x4000
	s_addc_u32 s27, s27, 0
	s_add_u32 s6, s28, 0x8000
	s_addc_u32 s7, s29, 0
	s_mov_b32 s28, 0
	s_add_i32 s40, s28, 2
	s_add_u32 s4, s26, 0x4000
	s_addc_u32 s5, s27, 0
	s_cmp_eq_u32 s58, s28
	s_cselect_b32 s34, s22, s4
	s_cselect_b32 s35, s23, s5
	s_cselect_b32 s30, s24, s6
	s_cselect_b32 s31, s25, s7
	s_add_u32 s28, s34, 0x4000
	s_addc_u32 s29, s35, 0
	s_add_i32 s4, 0, 0x10000
	s_add_i32 s41, 0, 0x14000
	v_add_u32_e32 v152, s4, v138
	v_add_u32_e32 v168, s41, v138
	ds_read_b128 v[140:143], v152
	ds_read_b128 v[144:147], v152 offset:1024
	ds_read_b128 v[148:151], v152 offset:2048
	ds_read_b128 v[152:155], v152 offset:3072
	ds_read_b128 v[156:159], v168
	ds_read_b128 v[160:163], v168 offset:1024
	ds_read_b128 v[164:167], v168 offset:2048
	ds_read_b128 v[168:171], v168 offset:3072
	v_lshl_add_u64 v[206:207], s[26:27], 0, v[132:133]
	s_add_i32 m0, s11, 0xc000
	ds_read_b128 v[172:175], v139
	ds_read_b128 v[176:179], v139 offset:1024
	ds_read_b128 v[180:183], v139 offset:2048
	ds_read_b128 v[184:187], v139 offset:3072
	ds_read_b128 v[190:193], v139 offset:4096
	ds_read_b128 v[194:197], v139 offset:5120
	ds_read_b128 v[198:201], v139 offset:6144
	ds_read_b128 v[202:205], v139 offset:7168
	global_load_lds_dwordx4 v[206:207], off
	v_lshl_add_u64 v[206:207], s[26:27], 0, v[134:135]
	s_add_i32 m0, s11, 0xe000
	s_nop 0
	global_load_lds_dwordx4 v[206:207], off
	s_waitcnt vmcnt(8)
	s_waitcnt lgkmcnt(0)
	s_barrier
	s_setprio 1
	v_mfma_f32_16x16x32_bf16 v[120:123], v[140:143], v[172:175], 0
	v_mfma_f32_16x16x32_bf16 v[124:127], v[148:151], v[172:175], 0
	v_mfma_f32_16x16x32_bf16 v[108:111], v[140:143], v[180:183], 0
	v_mfma_f32_16x16x32_bf16 v[104:107], v[148:151], v[180:183], 0
	v_mfma_f32_16x16x32_bf16 v[92:95], v[140:143], v[190:193], 0
	v_mfma_f32_16x16x32_bf16 v[88:91], v[148:151], v[190:193], 0
	v_mfma_f32_16x16x32_bf16 v[76:79], v[140:143], v[198:201], 0
	v_mfma_f32_16x16x32_bf16 v[72:75], v[148:151], v[198:201], 0
	v_mfma_f32_16x16x32_bf16 v[120:123], v[144:147], v[176:179], v[120:123]
	v_mfma_f32_16x16x32_bf16 v[124:127], v[152:155], v[176:179], v[124:127]
	v_mfma_f32_16x16x32_bf16 v[108:111], v[144:147], v[184:187], v[108:111]
	v_mfma_f32_16x16x32_bf16 v[104:107], v[152:155], v[184:187], v[104:107]
	v_mfma_f32_16x16x32_bf16 v[92:95], v[144:147], v[194:197], v[92:95]
	v_mfma_f32_16x16x32_bf16 v[88:91], v[152:155], v[194:197], v[88:91]
	v_mfma_f32_16x16x32_bf16 v[76:79], v[144:147], v[202:205], v[76:79]
	v_mfma_f32_16x16x32_bf16 v[72:75], v[152:155], v[202:205], v[72:75]
	s_setprio 0
	s_setprio 1
	v_mfma_f32_16x16x32_bf16 v[116:119], v[156:159], v[172:175], 0
	v_mfma_f32_16x16x32_bf16 v[112:115], v[164:167], v[172:175], 0
	v_mfma_f32_16x16x32_bf16 v[100:103], v[156:159], v[180:183], 0
	v_mfma_f32_16x16x32_bf16 v[96:99], v[164:167], v[180:183], 0
	v_mfma_f32_16x16x32_bf16 v[84:87], v[156:159], v[190:193], 0
	v_mfma_f32_16x16x32_bf16 v[80:83], v[164:167], v[190:193], 0
	v_mfma_f32_16x16x32_bf16 v[68:71], v[156:159], v[198:201], 0
	v_mfma_f32_16x16x32_bf16 v[64:67], v[164:167], v[198:201], 0
	v_mfma_f32_16x16x32_bf16 v[116:119], v[160:163], v[176:179], v[116:119]
	v_mfma_f32_16x16x32_bf16 v[112:115], v[168:171], v[176:179], v[112:115]
	v_mfma_f32_16x16x32_bf16 v[100:103], v[160:163], v[184:187], v[100:103]
	v_mfma_f32_16x16x32_bf16 v[96:99], v[168:171], v[184:187], v[96:99]
	v_mfma_f32_16x16x32_bf16 v[84:87], v[160:163], v[194:197], v[84:87]
	v_mfma_f32_16x16x32_bf16 v[80:83], v[168:171], v[194:197], v[80:83]
	v_mfma_f32_16x16x32_bf16 v[68:71], v[160:163], v[202:205], v[68:71]
	v_mfma_f32_16x16x32_bf16 v[64:67], v[168:171], v[202:205], v[64:67]
	s_setprio 0
	s_barrier
	s_add_i32 s4, s4, s0
	v_lshl_add_u64 v[206:207], s[30:31], 0, v[128:129]
	s_mov_b32 m0, s4
	ds_read_b128 v[172:175], v139 offset:16384
	ds_read_b128 v[176:179], v139 offset:17408
	ds_read_b128 v[180:183], v139 offset:18432
	ds_read_b128 v[184:187], v139 offset:19456
	ds_read_b128 v[190:193], v139 offset:20480
	ds_read_b128 v[194:197], v139 offset:21504
	ds_read_b128 v[198:201], v139 offset:22528
	ds_read_b128 v[202:205], v139 offset:23552
	global_load_lds_dwordx4 v[206:207], off
	s_add_i32 m0, s4, 0x2000
	s_add_u32 s4, s30, s12
	v_lshl_add_u64 v[206:207], s[30:31], 0, v[130:131]
	s_addc_u32 s5, s31, s13
	s_add_i32 s41, s41, s0
	global_load_lds_dwordx4 v[206:207], off
	v_lshl_add_u64 v[206:207], s[4:5], 0, v[128:129]
	s_mov_b32 m0, s41
	s_nop 0
	global_load_lds_dwordx4 v[206:207], off
	v_lshl_add_u64 v[206:207], s[4:5], 0, v[130:131]
	s_add_i32 m0, s41, 0x2000
	s_nop 0
	global_load_lds_dwordx4 v[206:207], off
	v_lshl_add_u64 v[206:207], s[34:35], 0, v[128:129]
	s_mov_b32 m0, s11
	s_nop 0
	global_load_lds_dwordx4 v[206:207], off
	v_lshl_add_u64 v[206:207], s[34:35], 0, v[130:131]
	s_mov_b32 m0, s48
	s_nop 0
	global_load_lds_dwordx4 v[206:207], off
	s_waitcnt vmcnt(8)
	s_waitcnt lgkmcnt(0)
	s_barrier
; #define PG8_STAGE(bufoff, gbase, voff) do { _Pragma("unroll") for (int _i = 0; _i < 2; ++_i) \
;         __builtin_amdgcn_global_load_lds((const unsigned*)((const char*)(gbase) + (voff)[_i]), (PG8_LAS unsigned*)(lds + (bufoff) + ldsw + _i * 8192), 16, 0, 0); } while (0)
; #define PG8_LDA(dst, b, h) do { _Pragma("unroll") for (int m = 0; m < 4; ++m) _Pragma("unroll") for (int k = 0; k < 2; ++k) dst[m][k] = *(const PG8_LAS bf16x8*)(lds + PG8_SA(b, h) + aoff + m * 2048 + k * 1024); } while (0)
; #define PG8_LDB(dst, b, h) do { _Pragma("unroll") for (int n = 0; n < 2; ++n) _Pragma("unroll") for (int k = 0; k < 2; ++k) dst[n][k] = *(const PG8_LAS bf16x8*)(lds + PG8_SB(b, h) + boff + n * 2048 + k * 1024); } while (0)
; #define PG8_MMA(ai, bj, At, Bt) do { __builtin_amdgcn_s_setprio(1); _Pragma("unroll") for (int m = 0; m < 4; ++m) _Pragma("unroll") for (int n = 0; n < 2; ++n) _Pragma("unroll") for (int k = 0; k < 2; ++k) \
;         acc[ai][bj][m][n] = __builtin_amdgcn_mfma_f32_16x16x32_bf16(Bt[n][k], At[m][k], acc[ai][bj][m][n], 0, 0, 0); __builtin_amdgcn_s_setprio(0); } while (0)
; #define PG8_WAIT_V(n) asm volatile("s_waitcnt vmcnt(" #n ")" ::: "memory")
; #define PG8_WAIT_L(n) asm volatile("s_waitcnt lgkmcnt(" #n ")" ::: "memory")
; #define PG8_BAR __builtin_amdgcn_s_barrier()
; #define PG8_SCHED __builtin_amdgcn_sched_barrier(0)
; template <class Epi, class Sched, bool ALIGN_EPI = false, bool SP2 = false>
; __device__ __forceinline__ void gemm_phase(PG8_LAS unsigned char* lds, const Gemm g, const Sched& S, const Epi& E, const int tid_in) {
;     ...
;             PG8_WAIT_V(8); PG8_WAIT_L(0); PG8_BAR; PG8_MMA(1, 0, At, B0); PG8_MMA(1, 1, At, B1); PG8_BAR; PG8_SCHED;
;             PG8_LDB(B0, 1, 0); PG8_LDB(B1, 1, 1); PG8_SCHED; PG8_LDA(At, 1, 0); PG8_STAGE(PG8_SA(0, 1), a2 + hstepA, voffA);
;             PG8_WAIT_V(8); PG8_WAIT_L(0); PG8_BAR; PG8_MMA(0, 0, At, B0); PG8_MMA(0, 1, At, B1); PG8_BAR; PG8_SCHED;
	s_setprio 1
	v_mfma_f32_16x16x32_bf16 v[60:63], v[140:143], v[172:175], 0
	v_mfma_f32_16x16x32_bf16 v[56:59], v[148:151], v[172:175], 0
	v_mfma_f32_16x16x32_bf16 v[44:47], v[140:143], v[180:183], 0
	v_mfma_f32_16x16x32_bf16 v[40:43], v[148:151], v[180:183], 0
	v_mfma_f32_16x16x32_bf16 v[28:31], v[140:143], v[190:193], 0
	v_mfma_f32_16x16x32_bf16 v[24:27], v[148:151], v[190:193], 0
	v_mfma_f32_16x16x32_bf16 v[12:15], v[140:143], v[198:201], 0
	v_mfma_f32_16x16x32_bf16 v[8:11], v[148:151], v[198:201], 0
	v_mfma_f32_16x16x32_bf16 v[60:63], v[144:147], v[176:179], v[60:63]
	v_mfma_f32_16x16x32_bf16 v[56:59], v[152:155], v[176:179], v[56:59]
	v_mfma_f32_16x16x32_bf16 v[44:47], v[144:147], v[184:187], v[44:47]
	v_mfma_f32_16x16x32_bf16 v[40:43], v[152:155], v[184:187], v[40:43]
	v_mfma_f32_16x16x32_bf16 v[28:31], v[144:147], v[194:197], v[28:31]
	v_mfma_f32_16x16x32_bf16 v[24:27], v[152:155], v[194:197], v[24:27]
	v_mfma_f32_16x16x32_bf16 v[12:15], v[144:147], v[202:205], v[12:15]
	v_mfma_f32_16x16x32_bf16 v[8:11], v[152:155], v[202:205], v[8:11]
	s_setprio 0
	s_setprio 1
	v_mfma_f32_16x16x32_bf16 v[52:55], v[156:159], v[172:175], 0
	v_mfma_f32_16x16x32_bf16 v[48:51], v[164:167], v[172:175], 0
	v_mfma_f32_16x16x32_bf16 v[36:39], v[156:159], v[180:183], 0
	v_mfma_f32_16x16x32_bf16 v[32:35], v[164:167], v[180:183], 0
	v_mfma_f32_16x16x32_bf16 v[20:23], v[156:159], v[190:193], 0
	v_mfma_f32_16x16x32_bf16 v[16:19], v[164:167], v[190:193], 0
	v_mfma_f32_16x16x32_bf16 v[4:7], v[156:159], v[198:201], 0
	v_mfma_f32_16x16x32_bf16 v[0:3], v[164:167], v[198:201], 0
	v_mfma_f32_16x16x32_bf16 v[52:55], v[160:163], v[176:179], v[52:55]
	v_mfma_f32_16x16x32_bf16 v[48:51], v[168:171], v[176:179], v[48:51]
	v_mfma_f32_16x16x32_bf16 v[36:39], v[160:163], v[184:187], v[36:39]
	v_mfma_f32_16x16x32_bf16 v[32:35], v[168:171], v[184:187], v[32:35]
	v_mfma_f32_16x16x32_bf16 v[20:23], v[160:163], v[194:197], v[20:23]
	v_mfma_f32_16x16x32_bf16 v[16:19], v[168:171], v[194:197], v[16:19]
	v_mfma_f32_16x16x32_bf16 v[4:7], v[160:163], v[202:205], v[4:7]
	v_mfma_f32_16x16x32_bf16 v[0:3], v[168:171], v[202:205], v[0:3]
	s_setprio 0
	s_barrier
	s_add_i32 s41, 0, 0x18000
	s_add_i32 s71, 0, 0x1c000
	v_add_u32_e32 v152, s41, v138
	v_add_u32_e32 v168, s71, v138
	ds_read_b128 v[140:143], v152
	ds_read_b128 v[144:147], v152 offset:1024
	ds_read_b128 v[148:151], v152 offset:2048
	ds_read_b128 v[152:155], v152 offset:3072
	ds_read_b128 v[156:159], v168
	ds_read_b128 v[160:163], v168 offset:1024
	ds_read_b128 v[164:167], v168 offset:2048
	ds_read_b128 v[168:171], v168 offset:3072
	s_add_u32 s4, s34, s12
	s_addc_u32 s5, s35, s13
	s_mov_b32 m0, s49
	v_lshl_add_u64 v[206:207], s[4:5], 0, v[128:129]
	ds_read_b128 v[172:175], v139 offset:32768
	ds_read_b128 v[176:179], v139 offset:33792
	ds_read_b128 v[180:183], v139 offset:34816
	ds_read_b128 v[184:187], v139 offset:35840
	ds_read_b128 v[190:193], v139 offset:36864
	ds_read_b128 v[194:197], v139 offset:37888
	ds_read_b128 v[198:201], v139 offset:38912
	ds_read_b128 v[202:205], v139 offset:39936
	global_load_lds_dwordx4 v[206:207], off
	v_lshl_add_u64 v[206:207], s[4:5], 0, v[130:131]
	s_mov_b32 m0, s50
	s_nop 0
	global_load_lds_dwordx4 v[206:207], off
	s_waitcnt vmcnt(8)
	s_waitcnt lgkmcnt(0)
	s_barrier
	s_setprio 1
	v_mfma_f32_16x16x32_bf16 v[120:123], v[140:143], v[172:175], v[120:123]
	v_mfma_f32_16x16x32_bf16 v[124:127], v[148:151], v[172:175], v[124:127]
	v_mfma_f32_16x16x32_bf16 v[108:111], v[140:143], v[180:183], v[108:111]
	v_mfma_f32_16x16x32_bf16 v[104:107], v[148:151], v[180:183], v[104:107]
	v_mfma_f32_16x16x32_bf16 v[92:95], v[140:143], v[190:193], v[92:95]
	v_mfma_f32_16x16x32_bf16 v[88:91], v[148:151], v[190:193], v[88:91]
	v_mfma_f32_16x16x32_bf16 v[76:79], v[140:143], v[198:201], v[76:79]
	v_mfma_f32_16x16x32_bf16 v[72:75], v[148:151], v[198:201], v[72:75]
	v_mfma_f32_16x16x32_bf16 v[120:123], v[144:147], v[176:179], v[120:123]
	v_mfma_f32_16x16x32_bf16 v[124:127], v[152:155], v[176:179], v[124:127]
	v_mfma_f32_16x16x32_bf16 v[108:111], v[144:147], v[184:187], v[108:111]
	v_mfma_f32_16x16x32_bf16 v[104:107], v[152:155], v[184:187], v[104:107]
	v_mfma_f32_16x16x32_bf16 v[92:95], v[144:147], v[194:197], v[92:95]
	v_mfma_f32_16x16x32_bf16 v[88:91], v[152:155], v[194:197], v[88:91]
	v_mfma_f32_16x16x32_bf16 v[76:79], v[144:147], v[202:205], v[76:79]
	v_mfma_f32_16x16x32_bf16 v[72:75], v[152:155], v[202:205], v[72:75]
	s_setprio 0
	s_setprio 1
	v_mfma_f32_16x16x32_bf16 v[116:119], v[156:159], v[172:175], v[116:119]
	v_mfma_f32_16x16x32_bf16 v[112:115], v[164:167], v[172:175], v[112:115]
	v_mfma_f32_16x16x32_bf16 v[100:103], v[156:159], v[180:183], v[100:103]
	v_mfma_f32_16x16x32_bf16 v[96:99], v[164:167], v[180:183], v[96:99]
	v_mfma_f32_16x16x32_bf16 v[84:87], v[156:159], v[190:193], v[84:87]
	v_mfma_f32_16x16x32_bf16 v[80:83], v[164:167], v[190:193], v[80:83]
	v_mfma_f32_16x16x32_bf16 v[68:71], v[156:159], v[198:201], v[68:71]
	v_mfma_f32_16x16x32_bf16 v[64:67], v[164:167], v[198:201], v[64:67]
	v_mfma_f32_16x16x32_bf16 v[116:119], v[160:163], v[176:179], v[116:119]
	v_mfma_f32_16x16x32_bf16 v[112:115], v[168:171], v[176:179], v[112:115]
	v_mfma_f32_16x16x32_bf16 v[100:103], v[160:163], v[184:187], v[100:103]
	v_mfma_f32_16x16x32_bf16 v[96:99], v[168:171], v[184:187], v[96:99]
	v_mfma_f32_16x16x32_bf16 v[84:87], v[160:163], v[194:197], v[84:87]
	v_mfma_f32_16x16x32_bf16 v[80:83], v[168:171], v[194:197], v[80:83]
	v_mfma_f32_16x16x32_bf16 v[68:71], v[160:163], v[202:205], v[68:71]
	v_mfma_f32_16x16x32_bf16 v[64:67], v[168:171], v[202:205], v[64:67]
	s_setprio 0
	s_barrier
; #define PG8_STAGE(bufoff, gbase, voff) do { _Pragma("unroll") for (int _i = 0; _i < 2; ++_i) \
;         __builtin_amdgcn_global_load_lds((const unsigned*)((const char*)(gbase) + (voff)[_i]), (PG8_LAS unsigned*)(lds + (bufoff) + ldsw + _i * 8192), 16, 0, 0); } while (0)
; #define PG8_LDA(dst, b, h) do { _Pragma("unroll") for (int m = 0; m < 4; ++m) _Pragma("unroll") for (int k = 0; k < 2; ++k) dst[m][k] = *(const PG8_LAS bf16x8*)(lds + PG8_SA(b, h) + aoff + m * 2048 + k * 1024); } while (0)
; #define PG8_LDB(dst, b, h) do { _Pragma("unroll") for (int n = 0; n < 2; ++n) _Pragma("unroll") for (int k = 0; k < 2; ++k) dst[n][k] = *(const PG8_LAS bf16x8*)(lds + PG8_SB(b, h) + boff + n * 2048 + k * 1024); } while (0)
; #define PG8_MMA(ai, bj, At, Bt) do { __builtin_amdgcn_s_setprio(1); _Pragma("unroll") for (int m = 0; m < 4; ++m) _Pragma("unroll") for (int n = 0; n < 2; ++n) _Pragma("unroll") for (int k = 0; k < 2; ++k) \
;         acc[ai][bj][m][n] = __builtin_amdgcn_mfma_f32_16x16x32_bf16(Bt[n][k], At[m][k], acc[ai][bj][m][n], 0, 0, 0); __builtin_amdgcn_s_setprio(0); } while (0)
; #define PG8_WAIT_V(n) asm volatile("s_waitcnt vmcnt(" #n ")" ::: "memory")
; #define PG8_BAR __builtin_amdgcn_s_barrier()
; template <class Epi, class Sched, bool ALIGN_EPI = false, bool SP2 = false>
; __device__ __forceinline__ void gemm_phase(PG8_LAS unsigned char* lds, const Gemm g, const Sched& S, const Epi& E, const int tid_in) {
;     ...
;         for (int t = 0; t < nt; t += 2) {
;             const bool last = (t == nt - 2);
;             const char* a1 = cA + (size_t)(t + 1) * kstepA;
;             const char* a2 = last ? nA : cA + (size_t)(t + 2) * kstepA; const char* b2 = last ? nB : cB + (size_t)(t + 2) * kstepB;
;             const char* a3 = a2 + kstepA; const char* b3 = b2 + kstepB;
;             if (last && has_next) S.a_ready(nxt);
;             if constexpr (SP2) {
;             PG8_LDB(B0, 0, 0); PG8_LDB(B1, 0, 1); PG8_SCHED; PG8_LDA(At, 0, 0); PG8_STAGE(PG8_SA(1, 1), a1 + hstepA, voffA);
;             PG8_WAIT_V(8); PG8_WAIT_L(0); PG8_BAR; PG8_MMA(0, 0, At, B0); PG8_MMA(0, 1, At, B1); PG8_BAR; PG8_SCHED;
;     ...
;             PG8_LDA(At, 1, 1); PG8_STAGE(PG8_SB(1, 0), b3, voffB); PG8_STAGE(PG8_SB(1, 1), b3 + hstepB, voffB); PG8_STAGE(PG8_SA(1, 0), a3, voffA);
;             PG8_WAIT_V(8); PG8_WAIT_L(0); PG8_BAR; PG8_MMA(1, 0, At, B0); PG8_MMA(1, 1, At, B1); PG8_BAR; PG8_SCHED;
	s_add_u32 s4, s30, 0x4000
	s_addc_u32 s5, s31, 0
	s_add_i32 s30, s41, s0
	v_lshl_add_u64 v[206:207], s[4:5], 0, v[128:129]
	s_mov_b32 m0, s30
	ds_read_b128 v[172:175], v139 offset:49152
	ds_read_b128 v[176:179], v139 offset:50176
	ds_read_b128 v[180:183], v139 offset:51200
	ds_read_b128 v[184:187], v139 offset:52224
	ds_read_b128 v[190:193], v139 offset:53248
	ds_read_b128 v[194:197], v139 offset:54272
	ds_read_b128 v[198:201], v139 offset:55296
	ds_read_b128 v[202:205], v139 offset:56320
	global_load_lds_dwordx4 v[206:207], off
	s_add_i32 m0, s30, 0x2000
	v_lshl_add_u64 v[206:207], s[4:5], 0, v[130:131]
	s_add_u32 s4, s4, s12
	s_addc_u32 s5, s5, s13
	s_add_i32 s30, s71, s0
	global_load_lds_dwordx4 v[206:207], off
	v_lshl_add_u64 v[206:207], s[4:5], 0, v[128:129]
	s_mov_b32 m0, s30
	s_nop 0
	global_load_lds_dwordx4 v[206:207], off
	v_lshl_add_u64 v[206:207], s[4:5], 0, v[130:131]
	s_add_i32 m0, s30, 0x2000
	s_nop 0
	global_load_lds_dwordx4 v[206:207], off
	v_lshl_add_u64 v[206:207], s[28:29], 0, v[128:129]
	s_mov_b32 m0, s56
	s_nop 0
	global_load_lds_dwordx4 v[206:207], off
	v_lshl_add_u64 v[206:207], s[28:29], 0, v[130:131]
	s_mov_b32 m0, s57
	s_nop 0
	global_load_lds_dwordx4 v[206:207], off
	s_waitcnt vmcnt(8)
	s_waitcnt lgkmcnt(0)
	s_barrier
	s_setprio 1
	v_mfma_f32_16x16x32_bf16 v[60:63], v[140:143], v[172:175], v[60:63]
	v_mfma_f32_16x16x32_bf16 v[56:59], v[148:151], v[172:175], v[56:59]
	v_mfma_f32_16x16x32_bf16 v[44:47], v[140:143], v[180:183], v[44:47]
	v_mfma_f32_16x16x32_bf16 v[40:43], v[148:151], v[180:183], v[40:43]
	v_mfma_f32_16x16x32_bf16 v[28:31], v[140:143], v[190:193], v[28:31]
	v_mfma_f32_16x16x32_bf16 v[24:27], v[148:151], v[190:193], v[24:27]
	v_mfma_f32_16x16x32_bf16 v[12:15], v[140:143], v[198:201], v[12:15]
	v_mfma_f32_16x16x32_bf16 v[8:11], v[148:151], v[198:201], v[8:11]
	v_mfma_f32_16x16x32_bf16 v[60:63], v[144:147], v[176:179], v[60:63]
	v_mfma_f32_16x16x32_bf16 v[56:59], v[152:155], v[176:179], v[56:59]
	v_mfma_f32_16x16x32_bf16 v[44:47], v[144:147], v[184:187], v[44:47]
	v_mfma_f32_16x16x32_bf16 v[40:43], v[152:155], v[184:187], v[40:43]
	v_mfma_f32_16x16x32_bf16 v[28:31], v[144:147], v[194:197], v[28:31]
	v_mfma_f32_16x16x32_bf16 v[24:27], v[152:155], v[194:197], v[24:27]
	v_mfma_f32_16x16x32_bf16 v[12:15], v[144:147], v[202:205], v[12:15]
	v_mfma_f32_16x16x32_bf16 v[8:11], v[152:155], v[202:205], v[8:11]
	s_setprio 0
	s_setprio 1
	v_mfma_f32_16x16x32_bf16 v[52:55], v[156:159], v[172:175], v[52:55]
	v_mfma_f32_16x16x32_bf16 v[48:51], v[164:167], v[172:175], v[48:51]
	v_mfma_f32_16x16x32_bf16 v[36:39], v[156:159], v[180:183], v[36:39]
	v_mfma_f32_16x16x32_bf16 v[32:35], v[164:167], v[180:183], v[32:35]
	v_mfma_f32_16x16x32_bf16 v[20:23], v[156:159], v[190:193], v[20:23]
	v_mfma_f32_16x16x32_bf16 v[16:19], v[164:167], v[190:193], v[16:19]
	v_mfma_f32_16x16x32_bf16 v[4:7], v[156:159], v[198:201], v[4:7]
	v_mfma_f32_16x16x32_bf16 v[0:3], v[164:167], v[198:201], v[0:3]
	v_mfma_f32_16x16x32_bf16 v[52:55], v[160:163], v[176:179], v[52:55]
	v_mfma_f32_16x16x32_bf16 v[48:51], v[168:171], v[176:179], v[48:51]
	v_mfma_f32_16x16x32_bf16 v[36:39], v[160:163], v[184:187], v[36:39]
	v_mfma_f32_16x16x32_bf16 v[32:35], v[168:171], v[184:187], v[32:35]
	v_mfma_f32_16x16x32_bf16 v[20:23], v[160:163], v[194:197], v[20:23]
	v_mfma_f32_16x16x32_bf16 v[16:19], v[168:171], v[194:197], v[16:19]
	v_mfma_f32_16x16x32_bf16 v[4:7], v[160:163], v[202:205], v[4:7]
	v_mfma_f32_16x16x32_bf16 v[0:3], v[168:171], v[202:205], v[0:3]
	s_setprio 0
	s_barrier
	s_add_u32 s26, s26, 0x8000
	s_addc_u32 s27, s27, 0
	s_add_u32 s6, s6, 0x8000
	s_addc_u32 s7, s7, 0
	s_cmp_ge_i32 s40, s10
	s_mov_b32 s28, s40
	s_cbranch_scc1 .LBB0_121
.LBB0_120:
	s_add_i32 s40, s28, 2
	s_add_u32 s4, s26, 0x4000
	s_addc_u32 s5, s27, 0
	s_cmp_eq_u32 s58, s28
	s_cselect_b32 s34, s22, s4
	s_cselect_b32 s35, s23, s5
	s_cselect_b32 s30, s24, s6
	s_cselect_b32 s31, s25, s7
	s_add_u32 s28, s34, 0x4000
	s_addc_u32 s29, s35, 0
	s_add_i32 s4, 0, 0x10000
	s_add_i32 s41, 0, 0x14000
	v_add_u32_e32 v152, s4, v138
	v_add_u32_e32 v168, s41, v138
	ds_read_b128 v[140:143], v152
	ds_read_b128 v[144:147], v152 offset:1024
	ds_read_b128 v[148:151], v152 offset:2048
	ds_read_b128 v[152:155], v152 offset:3072
	ds_read_b128 v[156:159], v168
	ds_read_b128 v[160:163], v168 offset:1024
	ds_read_b128 v[164:167], v168 offset:2048
	ds_read_b128 v[168:171], v168 offset:3072
	v_lshl_add_u64 v[206:207], s[26:27], 0, v[132:133]
	s_add_i32 m0, s11, 0xc000
	ds_read_b128 v[172:175], v139
	ds_read_b128 v[176:179], v139 offset:1024
	ds_read_b128 v[180:183], v139 offset:2048
	ds_read_b128 v[184:187], v139 offset:3072
	ds_read_b128 v[190:193], v139 offset:4096
	ds_read_b128 v[194:197], v139 offset:5120
	ds_read_b128 v[198:201], v139 offset:6144
	ds_read_b128 v[202:205], v139 offset:7168
	global_load_lds_dwordx4 v[206:207], off
	v_lshl_add_u64 v[206:207], s[26:27], 0, v[134:135]
	s_add_i32 m0, s11, 0xe000
	s_nop 0
	global_load_lds_dwordx4 v[206:207], off
	s_waitcnt vmcnt(8)
	s_waitcnt lgkmcnt(0)
	s_barrier
; #define PG8_STAGE(bufoff, gbase, voff) do { _Pragma("unroll") for (int _i = 0; _i < 2; ++_i) \
;         __builtin_amdgcn_global_load_lds((const unsigned*)((const char*)(gbase) + (voff)[_i]), (PG8_LAS unsigned*)(lds + (bufoff) + ldsw + _i * 8192), 16, 0, 0); } while (0)
; #define PG8_LDA(dst, b, h) do { _Pragma("unroll") for (int m = 0; m < 4; ++m) _Pragma("unroll") for (int k = 0; k < 2; ++k) dst[m][k] = *(const PG8_LAS bf16x8*)(lds + PG8_SA(b, h) + aoff + m * 2048 + k * 1024); } while (0)
; #define PG8_MMA(ai, bj, At, Bt) do { __builtin_amdgcn_s_setprio(1); _Pragma("unroll") for (int m = 0; m < 4; ++m) _Pragma("unroll") for (int n = 0; n < 2; ++n) _Pragma("unroll") for (int k = 0; k < 2; ++k) \
;         acc[ai][bj][m][n] = __builtin_amdgcn_mfma_f32_16x16x32_bf16(Bt[n][k], At[m][k], acc[ai][bj][m][n], 0, 0, 0); __builtin_amdgcn_s_setprio(0); } while (0)
; #define PG8_WAIT_V(n) asm volatile("s_waitcnt vmcnt(" #n ")" ::: "memory")
; #define PG8_WAIT_L(n) asm volatile("s_waitcnt lgkmcnt(" #n ")" ::: "memory")
; #define PG8_BAR __builtin_amdgcn_s_barrier()
; #define PG8_SCHED __builtin_amdgcn_sched_barrier(0)
; template <class Epi, class Sched, bool ALIGN_EPI = false, bool SP2 = false>
; __device__ __forceinline__ void gemm_phase(PG8_LAS unsigned char* lds, const Gemm g, const Sched& S, const Epi& E, const int tid_in) {
;     ...
;             PG8_WAIT_V(8); PG8_WAIT_L(0); PG8_BAR; PG8_MMA(0, 0, At, B0); PG8_MMA(0, 1, At, B1); PG8_BAR; PG8_SCHED;
;             PG8_LDA(At, 0, 1); PG8_STAGE(PG8_SB(0, 0), b2, voffB); PG8_STAGE(PG8_SB(0, 1), b2 + hstepB, voffB); PG8_STAGE(PG8_SA(0, 0), a2, voffA);
;             PG8_WAIT_V(8); PG8_WAIT_L(0); PG8_BAR; PG8_MMA(1, 0, At, B0); PG8_MMA(1, 1, At, B1); PG8_BAR; PG8_SCHED;
	s_setprio 1
	v_mfma_f32_16x16x32_bf16 v[120:123], v[140:143], v[172:175], v[120:123]
	v_mfma_f32_16x16x32_bf16 v[124:127], v[148:151], v[172:175], v[124:127]
	v_mfma_f32_16x16x32_bf16 v[108:111], v[140:143], v[180:183], v[108:111]
	v_mfma_f32_16x16x32_bf16 v[104:107], v[148:151], v[180:183], v[104:107]
	v_mfma_f32_16x16x32_bf16 v[92:95], v[140:143], v[190:193], v[92:95]
	v_mfma_f32_16x16x32_bf16 v[88:91], v[148:151], v[190:193], v[88:91]
	v_mfma_f32_16x16x32_bf16 v[76:79], v[140:143], v[198:201], v[76:79]
	v_mfma_f32_16x16x32_bf16 v[72:75], v[148:151], v[198:201], v[72:75]
	v_mfma_f32_16x16x32_bf16 v[120:123], v[144:147], v[176:179], v[120:123]
	v_mfma_f32_16x16x32_bf16 v[124:127], v[152:155], v[176:179], v[124:127]
	v_mfma_f32_16x16x32_bf16 v[108:111], v[144:147], v[184:187], v[108:111]
	v_mfma_f32_16x16x32_bf16 v[104:107], v[152:155], v[184:187], v[104:107]
	v_mfma_f32_16x16x32_bf16 v[92:95], v[144:147], v[194:197], v[92:95]
	v_mfma_f32_16x16x32_bf16 v[88:91], v[152:155], v[194:197], v[88:91]
	v_mfma_f32_16x16x32_bf16 v[76:79], v[144:147], v[202:205], v[76:79]
	v_mfma_f32_16x16x32_bf16 v[72:75], v[152:155], v[202:205], v[72:75]
	s_setprio 0
	s_setprio 1
	v_mfma_f32_16x16x32_bf16 v[116:119], v[156:159], v[172:175], v[116:119]
	v_mfma_f32_16x16x32_bf16 v[112:115], v[164:167], v[172:175], v[112:115]
	v_mfma_f32_16x16x32_bf16 v[100:103], v[156:159], v[180:183], v[100:103]
	v_mfma_f32_16x16x32_bf16 v[96:99], v[164:167], v[180:183], v[96:99]
	v_mfma_f32_16x16x32_bf16 v[84:87], v[156:159], v[190:193], v[84:87]
	v_mfma_f32_16x16x32_bf16 v[80:83], v[164:167], v[190:193], v[80:83]
	v_mfma_f32_16x16x32_bf16 v[68:71], v[156:159], v[198:201], v[68:71]
	v_mfma_f32_16x16x32_bf16 v[64:67], v[164:167], v[198:201], v[64:67]
	v_mfma_f32_16x16x32_bf16 v[116:119], v[160:163], v[176:179], v[116:119]
	v_mfma_f32_16x16x32_bf16 v[112:115], v[168:171], v[176:179], v[112:115]
	v_mfma_f32_16x16x32_bf16 v[100:103], v[160:163], v[184:187], v[100:103]
	v_mfma_f32_16x16x32_bf16 v[96:99], v[168:171], v[184:187], v[96:99]
	v_mfma_f32_16x16x32_bf16 v[84:87], v[160:163], v[194:197], v[84:87]
	v_mfma_f32_16x16x32_bf16 v[80:83], v[168:171], v[194:197], v[80:83]
	v_mfma_f32_16x16x32_bf16 v[68:71], v[160:163], v[202:205], v[68:71]
	v_mfma_f32_16x16x32_bf16 v[64:67], v[168:171], v[202:205], v[64:67]
	s_setprio 0
	s_barrier
	s_add_i32 s4, s4, s0
	v_lshl_add_u64 v[206:207], s[30:31], 0, v[128:129]
	s_mov_b32 m0, s4
	ds_read_b128 v[172:175], v139 offset:16384
	ds_read_b128 v[176:179], v139 offset:17408
	ds_read_b128 v[180:183], v139 offset:18432
	ds_read_b128 v[184:187], v139 offset:19456
	ds_read_b128 v[190:193], v139 offset:20480
	ds_read_b128 v[194:197], v139 offset:21504
	ds_read_b128 v[198:201], v139 offset:22528
	ds_read_b128 v[202:205], v139 offset:23552
	global_load_lds_dwordx4 v[206:207], off
	s_add_i32 m0, s4, 0x2000
	s_add_u32 s4, s30, s12
	v_lshl_add_u64 v[206:207], s[30:31], 0, v[130:131]
	s_addc_u32 s5, s31, s13
	s_add_i32 s41, s41, s0
	global_load_lds_dwordx4 v[206:207], off
	v_lshl_add_u64 v[206:207], s[4:5], 0, v[128:129]
	s_mov_b32 m0, s41
	s_nop 0
	global_load_lds_dwordx4 v[206:207], off
	v_lshl_add_u64 v[206:207], s[4:5], 0, v[130:131]
	s_add_i32 m0, s41, 0x2000
	s_nop 0
	global_load_lds_dwordx4 v[206:207], off
	v_lshl_add_u64 v[206:207], s[34:35], 0, v[128:129]
	s_mov_b32 m0, s11
	s_nop 0
	global_load_lds_dwordx4 v[206:207], off
	v_lshl_add_u64 v[206:207], s[34:35], 0, v[130:131]
	s_mov_b32 m0, s48
	s_nop 0
	global_load_lds_dwordx4 v[206:207], off
	s_waitcnt vmcnt(8)
	s_waitcnt lgkmcnt(0)
	s_barrier
	s_setprio 1
	v_mfma_f32_16x16x32_bf16 v[60:63], v[140:143], v[172:175], v[60:63]
	v_mfma_f32_16x16x32_bf16 v[56:59], v[148:151], v[172:175], v[56:59]
	v_mfma_f32_16x16x32_bf16 v[44:47], v[140:143], v[180:183], v[44:47]
	v_mfma_f32_16x16x32_bf16 v[40:43], v[148:151], v[180:183], v[40:43]
	v_mfma_f32_16x16x32_bf16 v[28:31], v[140:143], v[190:193], v[28:31]
	v_mfma_f32_16x16x32_bf16 v[24:27], v[148:151], v[190:193], v[24:27]
	v_mfma_f32_16x16x32_bf16 v[12:15], v[140:143], v[198:201], v[12:15]
	v_mfma_f32_16x16x32_bf16 v[8:11], v[148:151], v[198:201], v[8:11]
	v_mfma_f32_16x16x32_bf16 v[60:63], v[144:147], v[176:179], v[60:63]
	v_mfma_f32_16x16x32_bf16 v[56:59], v[152:155], v[176:179], v[56:59]
	v_mfma_f32_16x16x32_bf16 v[44:47], v[144:147], v[184:187], v[44:47]
	v_mfma_f32_16x16x32_bf16 v[40:43], v[152:155], v[184:187], v[40:43]
	v_mfma_f32_16x16x32_bf16 v[28:31], v[144:147], v[194:197], v[28:31]
	v_mfma_f32_16x16x32_bf16 v[24:27], v[152:155], v[194:197], v[24:27]
	v_mfma_f32_16x16x32_bf16 v[12:15], v[144:147], v[202:205], v[12:15]
	v_mfma_f32_16x16x32_bf16 v[8:11], v[152:155], v[202:205], v[8:11]
	s_setprio 0
	s_setprio 1
	v_mfma_f32_16x16x32_bf16 v[52:55], v[156:159], v[172:175], v[52:55]
	v_mfma_f32_16x16x32_bf16 v[48:51], v[164:167], v[172:175], v[48:51]
	v_mfma_f32_16x16x32_bf16 v[36:39], v[156:159], v[180:183], v[36:39]
	v_mfma_f32_16x16x32_bf16 v[32:35], v[164:167], v[180:183], v[32:35]
	v_mfma_f32_16x16x32_bf16 v[20:23], v[156:159], v[190:193], v[20:23]
	v_mfma_f32_16x16x32_bf16 v[16:19], v[164:167], v[190:193], v[16:19]
	v_mfma_f32_16x16x32_bf16 v[4:7], v[156:159], v[198:201], v[4:7]
	v_mfma_f32_16x16x32_bf16 v[0:3], v[164:167], v[198:201], v[0:3]
	v_mfma_f32_16x16x32_bf16 v[52:55], v[160:163], v[176:179], v[52:55]
	v_mfma_f32_16x16x32_bf16 v[48:51], v[168:171], v[176:179], v[48:51]
	v_mfma_f32_16x16x32_bf16 v[36:39], v[160:163], v[184:187], v[36:39]
	v_mfma_f32_16x16x32_bf16 v[32:35], v[168:171], v[184:187], v[32:35]
	v_mfma_f32_16x16x32_bf16 v[20:23], v[160:163], v[194:197], v[20:23]
	v_mfma_f32_16x16x32_bf16 v[16:19], v[168:171], v[194:197], v[16:19]
	v_mfma_f32_16x16x32_bf16 v[4:7], v[160:163], v[202:205], v[4:7]
	v_mfma_f32_16x16x32_bf16 v[0:3], v[168:171], v[202:205], v[0:3]
	s_setprio 0
	s_barrier
; #define PG8_STAGE(bufoff, gbase, voff) do { _Pragma("unroll") for (int _i = 0; _i < 2; ++_i) \
;         __builtin_amdgcn_global_load_lds((const unsigned*)((const char*)(gbase) + (voff)[_i]), (PG8_LAS unsigned*)(lds + (bufoff) + ldsw + _i * 8192), 16, 0, 0); } while (0)
; #define PG8_LDA(dst, b, h) do { _Pragma("unroll") for (int m = 0; m < 4; ++m) _Pragma("unroll") for (int k = 0; k < 2; ++k) dst[m][k] = *(const PG8_LAS bf16x8*)(lds + PG8_SA(b, h) + aoff + m * 2048 + k * 1024); } while (0)
; #define PG8_LDB(dst, b, h) do { _Pragma("unroll") for (int n = 0; n < 2; ++n) _Pragma("unroll") for (int k = 0; k < 2; ++k) dst[n][k] = *(const PG8_LAS bf16x8*)(lds + PG8_SB(b, h) + boff + n * 2048 + k * 1024); } while (0)
; #define PG8_MMA(ai, bj, At, Bt) do { __builtin_amdgcn_s_setprio(1); _Pragma("unroll") for (int m = 0; m < 4; ++m) _Pragma("unroll") for (int n = 0; n < 2; ++n) _Pragma("unroll") for (int k = 0; k < 2; ++k) \
;         acc[ai][bj][m][n] = __builtin_amdgcn_mfma_f32_16x16x32_bf16(Bt[n][k], At[m][k], acc[ai][bj][m][n], 0, 0, 0); __builtin_amdgcn_s_setprio(0); } while (0)
; #define PG8_WAIT_V(n) asm volatile("s_waitcnt vmcnt(" #n ")" ::: "memory")
; #define PG8_WAIT_L(n) asm volatile("s_waitcnt lgkmcnt(" #n ")" ::: "memory")
; #define PG8_BAR __builtin_amdgcn_s_barrier()
; #define PG8_SCHED __builtin_amdgcn_sched_barrier(0)
; template <class Epi, class Sched, bool ALIGN_EPI = false, bool SP2 = false>
; __device__ __forceinline__ void gemm_phase(PG8_LAS unsigned char* lds, const Gemm g, const Sched& S, const Epi& E, const int tid_in) {
;     ...
;             PG8_LDB(B0, 1, 0); PG8_LDB(B1, 1, 1); PG8_SCHED; PG8_LDA(At, 1, 0); PG8_STAGE(PG8_SA(0, 1), a2 + hstepA, voffA);
;             PG8_WAIT_V(8); PG8_WAIT_L(0); PG8_BAR; PG8_MMA(0, 0, At, B0); PG8_MMA(0, 1, At, B1); PG8_BAR; PG8_SCHED;
	s_add_i32 s41, 0, 0x18000
	s_add_i32 s71, 0, 0x1c000
	v_add_u32_e32 v152, s41, v138
	v_add_u32_e32 v168, s71, v138
	ds_read_b128 v[140:143], v152
	ds_read_b128 v[144:147], v152 offset:1024
	ds_read_b128 v[148:151], v152 offset:2048
	ds_read_b128 v[152:155], v152 offset:3072
	ds_read_b128 v[156:159], v168
	ds_read_b128 v[160:163], v168 offset:1024
	ds_read_b128 v[164:167], v168 offset:2048
	ds_read_b128 v[168:171], v168 offset:3072
	s_add_u32 s4, s34, s12
	s_addc_u32 s5, s35, s13
	s_mov_b32 m0, s49
	v_lshl_add_u64 v[206:207], s[4:5], 0, v[128:129]
	ds_read_b128 v[172:175], v139 offset:32768
	ds_read_b128 v[176:179], v139 offset:33792
	ds_read_b128 v[180:183], v139 offset:34816
	ds_read_b128 v[184:187], v139 offset:35840
	ds_read_b128 v[190:193], v139 offset:36864
	ds_read_b128 v[194:197], v139 offset:37888
	ds_read_b128 v[198:201], v139 offset:38912
	ds_read_b128 v[202:205], v139 offset:39936
	global_load_lds_dwordx4 v[206:207], off
	v_lshl_add_u64 v[206:207], s[4:5], 0, v[130:131]
	s_mov_b32 m0, s50
	s_nop 0
	global_load_lds_dwordx4 v[206:207], off
	s_waitcnt vmcnt(8)
	s_waitcnt lgkmcnt(0)
	s_barrier
	s_setprio 1
	v_mfma_f32_16x16x32_bf16 v[120:123], v[140:143], v[172:175], v[120:123]
	v_mfma_f32_16x16x32_bf16 v[124:127], v[148:151], v[172:175], v[124:127]
	v_mfma_f32_16x16x32_bf16 v[108:111], v[140:143], v[180:183], v[108:111]
	v_mfma_f32_16x16x32_bf16 v[104:107], v[148:151], v[180:183], v[104:107]
	v_mfma_f32_16x16x32_bf16 v[92:95], v[140:143], v[190:193], v[92:95]
	v_mfma_f32_16x16x32_bf16 v[88:91], v[148:151], v[190:193], v[88:91]
	v_mfma_f32_16x16x32_bf16 v[76:79], v[140:143], v[198:201], v[76:79]
	v_mfma_f32_16x16x32_bf16 v[72:75], v[148:151], v[198:201], v[72:75]
	v_mfma_f32_16x16x32_bf16 v[120:123], v[144:147], v[176:179], v[120:123]
	v_mfma_f32_16x16x32_bf16 v[124:127], v[152:155], v[176:179], v[124:127]
	v_mfma_f32_16x16x32_bf16 v[108:111], v[144:147], v[184:187], v[108:111]
	v_mfma_f32_16x16x32_bf16 v[104:107], v[152:155], v[184:187], v[104:107]
	v_mfma_f32_16x16x32_bf16 v[92:95], v[144:147], v[194:197], v[92:95]
	v_mfma_f32_16x16x32_bf16 v[88:91], v[152:155], v[194:197], v[88:91]
	v_mfma_f32_16x16x32_bf16 v[76:79], v[144:147], v[202:205], v[76:79]
	v_mfma_f32_16x16x32_bf16 v[72:75], v[152:155], v[202:205], v[72:75]
	s_setprio 0
	s_setprio 1
	v_mfma_f32_16x16x32_bf16 v[116:119], v[156:159], v[172:175], v[116:119]
	v_mfma_f32_16x16x32_bf16 v[112:115], v[164:167], v[172:175], v[112:115]
	v_mfma_f32_16x16x32_bf16 v[100:103], v[156:159], v[180:183], v[100:103]
	v_mfma_f32_16x16x32_bf16 v[96:99], v[164:167], v[180:183], v[96:99]
	v_mfma_f32_16x16x32_bf16 v[84:87], v[156:159], v[190:193], v[84:87]
	v_mfma_f32_16x16x32_bf16 v[80:83], v[164:167], v[190:193], v[80:83]
	v_mfma_f32_16x16x32_bf16 v[68:71], v[156:159], v[198:201], v[68:71]
	v_mfma_f32_16x16x32_bf16 v[64:67], v[164:167], v[198:201], v[64:67]
	v_mfma_f32_16x16x32_bf16 v[116:119], v[160:163], v[176:179], v[116:119]
	v_mfma_f32_16x16x32_bf16 v[112:115], v[168:171], v[176:179], v[112:115]
	v_mfma_f32_16x16x32_bf16 v[100:103], v[160:163], v[184:187], v[100:103]
	v_mfma_f32_16x16x32_bf16 v[96:99], v[168:171], v[184:187], v[96:99]
	v_mfma_f32_16x16x32_bf16 v[84:87], v[160:163], v[194:197], v[84:87]
	v_mfma_f32_16x16x32_bf16 v[80:83], v[168:171], v[194:197], v[80:83]
	v_mfma_f32_16x16x32_bf16 v[68:71], v[160:163], v[202:205], v[68:71]
	v_mfma_f32_16x16x32_bf16 v[64:67], v[168:171], v[202:205], v[64:67]
	s_setprio 0
	s_barrier
; #define PG8_STAGE(bufoff, gbase, voff) do { _Pragma("unroll") for (int _i = 0; _i < 2; ++_i) \
;         __builtin_amdgcn_global_load_lds((const unsigned*)((const char*)(gbase) + (voff)[_i]), (PG8_LAS unsigned*)(lds + (bufoff) + ldsw + _i * 8192), 16, 0, 0); } while (0)
; #define PG8_LDA(dst, b, h) do { _Pragma("unroll") for (int m = 0; m < 4; ++m) _Pragma("unroll") for (int k = 0; k < 2; ++k) dst[m][k] = *(const PG8_LAS bf16x8*)(lds + PG8_SA(b, h) + aoff + m * 2048 + k * 1024); } while (0)
; #define PG8_MMA(ai, bj, At, Bt) do { __builtin_amdgcn_s_setprio(1); _Pragma("unroll") for (int m = 0; m < 4; ++m) _Pragma("unroll") for (int n = 0; n < 2; ++n) _Pragma("unroll") for (int k = 0; k < 2; ++k) \
;         acc[ai][bj][m][n] = __builtin_amdgcn_mfma_f32_16x16x32_bf16(Bt[n][k], At[m][k], acc[ai][bj][m][n], 0, 0, 0); __builtin_amdgcn_s_setprio(0); } while (0)
; #define PG8_WAIT_V(n) asm volatile("s_waitcnt vmcnt(" #n ")" ::: "memory")
; #define PG8_WAIT_L(n) asm volatile("s_waitcnt lgkmcnt(" #n ")" ::: "memory")
; #define PG8_BAR __builtin_amdgcn_s_barrier()
; #define PG8_SCHED __builtin_amdgcn_sched_barrier(0)
; template <class Epi, class Sched, bool ALIGN_EPI = false, bool SP2 = false>
; __device__ __forceinline__ void gemm_phase(PG8_LAS unsigned char* lds, const Gemm g, const Sched& S, const Epi& E, const int tid_in) {
;     ...
;         for (int t = 0; t < nt; t += 2) {
;     ...
;             PG8_LDA(At, 1, 1); PG8_STAGE(PG8_SB(1, 0), b3, voffB); PG8_STAGE(PG8_SB(1, 1), b3 + hstepB, voffB); PG8_STAGE(PG8_SA(1, 0), a3, voffA);
;             PG8_WAIT_V(8); PG8_WAIT_L(0); PG8_BAR; PG8_MMA(1, 0, At, B0); PG8_MMA(1, 1, At, B1); PG8_BAR; PG8_SCHED;
	s_add_u32 s4, s30, 0x4000
	s_addc_u32 s5, s31, 0
	s_add_i32 s30, s41, s0
	v_lshl_add_u64 v[206:207], s[4:5], 0, v[128:129]
	s_mov_b32 m0, s30
	ds_read_b128 v[172:175], v139 offset:49152
	ds_read_b128 v[176:179], v139 offset:50176
	ds_read_b128 v[180:183], v139 offset:51200
	ds_read_b128 v[184:187], v139 offset:52224
	ds_read_b128 v[190:193], v139 offset:53248
	ds_read_b128 v[194:197], v139 offset:54272
	ds_read_b128 v[198:201], v139 offset:55296
	ds_read_b128 v[202:205], v139 offset:56320
	global_load_lds_dwordx4 v[206:207], off
	s_add_i32 m0, s30, 0x2000
	v_lshl_add_u64 v[206:207], s[4:5], 0, v[130:131]
	s_add_u32 s4, s4, s12
	s_addc_u32 s5, s5, s13
	s_add_i32 s30, s71, s0
	global_load_lds_dwordx4 v[206:207], off
	v_lshl_add_u64 v[206:207], s[4:5], 0, v[128:129]
	s_mov_b32 m0, s30
	s_nop 0
	global_load_lds_dwordx4 v[206:207], off
	v_lshl_add_u64 v[206:207], s[4:5], 0, v[130:131]
	s_add_i32 m0, s30, 0x2000
	s_nop 0
	global_load_lds_dwordx4 v[206:207], off
	v_lshl_add_u64 v[206:207], s[28:29], 0, v[128:129]
	s_mov_b32 m0, s56
	s_nop 0
	global_load_lds_dwordx4 v[206:207], off
	v_lshl_add_u64 v[206:207], s[28:29], 0, v[130:131]
	s_mov_b32 m0, s57
	s_nop 0
	global_load_lds_dwordx4 v[206:207], off
	s_waitcnt vmcnt(8)
	s_waitcnt lgkmcnt(0)
	s_barrier
	s_setprio 1
	v_mfma_f32_16x16x32_bf16 v[60:63], v[140:143], v[172:175], v[60:63]
	v_mfma_f32_16x16x32_bf16 v[56:59], v[148:151], v[172:175], v[56:59]
	v_mfma_f32_16x16x32_bf16 v[44:47], v[140:143], v[180:183], v[44:47]
	v_mfma_f32_16x16x32_bf16 v[40:43], v[148:151], v[180:183], v[40:43]
	v_mfma_f32_16x16x32_bf16 v[28:31], v[140:143], v[190:193], v[28:31]
	v_mfma_f32_16x16x32_bf16 v[24:27], v[148:151], v[190:193], v[24:27]
	v_mfma_f32_16x16x32_bf16 v[12:15], v[140:143], v[198:201], v[12:15]
	v_mfma_f32_16x16x32_bf16 v[8:11], v[148:151], v[198:201], v[8:11]
	v_mfma_f32_16x16x32_bf16 v[60:63], v[144:147], v[176:179], v[60:63]
	v_mfma_f32_16x16x32_bf16 v[56:59], v[152:155], v[176:179], v[56:59]
	v_mfma_f32_16x16x32_bf16 v[44:47], v[144:147], v[184:187], v[44:47]
	v_mfma_f32_16x16x32_bf16 v[40:43], v[152:155], v[184:187], v[40:43]
	v_mfma_f32_16x16x32_bf16 v[28:31], v[144:147], v[194:197], v[28:31]
	v_mfma_f32_16x16x32_bf16 v[24:27], v[152:155], v[194:197], v[24:27]
	v_mfma_f32_16x16x32_bf16 v[12:15], v[144:147], v[202:205], v[12:15]
	v_mfma_f32_16x16x32_bf16 v[8:11], v[152:155], v[202:205], v[8:11]
	s_setprio 0
	s_setprio 1
	v_mfma_f32_16x16x32_bf16 v[52:55], v[156:159], v[172:175], v[52:55]
	v_mfma_f32_16x16x32_bf16 v[48:51], v[164:167], v[172:175], v[48:51]
	v_mfma_f32_16x16x32_bf16 v[36:39], v[156:159], v[180:183], v[36:39]
	v_mfma_f32_16x16x32_bf16 v[32:35], v[164:167], v[180:183], v[32:35]
	v_mfma_f32_16x16x32_bf16 v[20:23], v[156:159], v[190:193], v[20:23]
	v_mfma_f32_16x16x32_bf16 v[16:19], v[164:167], v[190:193], v[16:19]
	v_mfma_f32_16x16x32_bf16 v[4:7], v[156:159], v[198:201], v[4:7]
	v_mfma_f32_16x16x32_bf16 v[0:3], v[164:167], v[198:201], v[0:3]
	v_mfma_f32_16x16x32_bf16 v[52:55], v[160:163], v[176:179], v[52:55]
	v_mfma_f32_16x16x32_bf16 v[48:51], v[168:171], v[176:179], v[48:51]
	v_mfma_f32_16x16x32_bf16 v[36:39], v[160:163], v[184:187], v[36:39]
	v_mfma_f32_16x16x32_bf16 v[32:35], v[168:171], v[184:187], v[32:35]
	v_mfma_f32_16x16x32_bf16 v[20:23], v[160:163], v[194:197], v[20:23]
	v_mfma_f32_16x16x32_bf16 v[16:19], v[168:171], v[194:197], v[16:19]
	v_mfma_f32_16x16x32_bf16 v[4:7], v[160:163], v[202:205], v[4:7]
	v_mfma_f32_16x16x32_bf16 v[0:3], v[168:171], v[202:205], v[0:3]
	s_setprio 0
	s_barrier
	s_add_u32 s26, s26, 0x8000
	s_addc_u32 s27, s27, 0
	s_add_u32 s6, s6, 0x8000
	s_addc_u32 s7, s7, 0
	s_cmp_ge_i32 s40, s10
	s_mov_b32 s28, s40
	s_cbranch_scc0 .LBB0_120

; #define PG8_STAGE(bufoff, gbase, voff) do { _Pragma("unroll") for (int _i = 0; _i < 2; ++_i) \
;         __builtin_amdgcn_global_load_lds((const unsigned*)((const char*)(gbase) + (voff)[_i]), (PG8_LAS unsigned*)(lds + (bufoff) + ldsw + _i * 8192), 16, 0, 0); } while (0)
; #define PG8_LDA(dst, b, h) do { _Pragma("unroll") for (int m = 0; m < 4; ++m) _Pragma("unroll") for (int k = 0; k < 2; ++k) dst[m][k] = *(const PG8_LAS bf16x8*)(lds + PG8_SA(b, h) + aoff + m * 2048 + k * 1024); } while (0)
; #define PG8_LDB(dst, b, h) do { _Pragma("unroll") for (int n = 0; n < 2; ++n) _Pragma("unroll") for (int k = 0; k < 2; ++k) dst[n][k] = *(const PG8_LAS bf16x8*)(lds + PG8_SB(b, h) + boff + n * 2048 + k * 1024); } while (0)
; #define PG8_MMA(ai, bj, At, Bt) do { __builtin_amdgcn_s_setprio(1); _Pragma("unroll") for (int m = 0; m < 4; ++m) _Pragma("unroll") for (int n = 0; n < 2; ++n) _Pragma("unroll") for (int k = 0; k < 2; ++k) \
;         acc[ai][bj][m][n] = __builtin_amdgcn_mfma_f32_16x16x32_bf16(Bt[n][k], At[m][k], acc[ai][bj][m][n], 0, 0, 0); __builtin_amdgcn_s_setprio(0); } while (0)
; #define PG8_WAIT_V(n) asm volatile("s_waitcnt vmcnt(" #n ")" ::: "memory")
; #define PG8_WAIT_L(n) asm volatile("s_waitcnt lgkmcnt(" #n ")" ::: "memory")
; template <class Epi, class Sched, bool ALIGN_EPI = false, bool SP2 = false>
; __device__ __forceinline__ void gemm_phase(PG8_LAS unsigned char* lds, const Gemm g, const Sched& S, const Epi& E, const int tid_in) {
;     ...
;             const bool last = (t == nt - 2);
;             const char* a1 = cA + (size_t)(t + 1) * kstepA;
;             const char* a2 = last ? nA : cA + (size_t)(t + 2) * kstepA; const char* b2 = last ? nB : cB + (size_t)(t + 2) * kstepB;
;             const char* a3 = a2 + kstepA; const char* b3 = b2 + kstepB;
;             if (last && has_next) S.a_ready(nxt);
;             if constexpr (SP2) {
;             PG8_LDB(B0, 0, 0); PG8_LDB(B1, 0, 1); PG8_SCHED; PG8_LDA(At, 0, 0); PG8_STAGE(PG8_SA(1, 1), a1 + hstepA, voffA);
;             PG8_WAIT_V(8); PG8_WAIT_L(0); PG8_BAR; PG8_MMA(0, 0, At, B0); PG8_MMA(0, 1, At, B1); PG8_BAR; PG8_SCHED;
;             PG8_LDA(At, 0, 1); PG8_STAGE(PG8_SB(0, 0), b2, voffB); PG8_STAGE(PG8_SB(0, 1), b2 + hstepB, voffB); PG8_STAGE(PG8_SA(0, 0), a2, voffA);
;             PG8_WAIT_V(8); PG8_WAIT_L(0); PG8_BAR; PG8_MMA(1, 0, At, B0); PG8_MMA(1, 1, At, B1); PG8_BAR; PG8_SCHED;
.LBB0_143:
	s_andn2_b64 vcc, exec, s[18:19]
	s_cbranch_vccnz .Lzero_acc_2
	s_add_u32 s26, s26, 0x4000
	s_addc_u32 s27, s27, 0
	s_add_u32 s6, s28, 0x8000
	s_addc_u32 s7, s29, 0
	s_mov_b32 s28, 0
	s_add_i32 s40, s28, 2
	s_add_u32 s4, s26, 0x4000
	s_addc_u32 s5, s27, 0
	s_cmp_eq_u32 s43, s28
	s_cselect_b32 s34, s22, s4
	s_cselect_b32 s35, s23, s5
	s_cselect_b32 s30, s24, s6
	s_cselect_b32 s31, s25, s7
	s_add_u32 s28, s34, 0x4000
	s_addc_u32 s29, s35, 0
	s_add_i32 s4, 0, 0x10000
	s_add_i32 s41, 0, 0x14000
	v_add_u32_e32 v140, s4, v190
	v_add_u32_e32 v166, s41, v190
	ds_read_b128 v[128:131], v140
	ds_read_b128 v[132:135], v140 offset:1024
	ds_read_b128 v[136:139], v140 offset:2048
	ds_read_b128 v[140:143], v140 offset:3072
	ds_read_b128 v[144:147], v166
	ds_read_b128 v[148:151], v166 offset:1024
	ds_read_b128 v[152:155], v166 offset:2048
	ds_read_b128 v[166:169], v166 offset:3072
	v_lshl_add_u64 v[186:187], s[26:27], 0, v[162:163]
	s_add_i32 m0, s1, 0xc000
	ds_read_b128 v[170:173], v194
	ds_read_b128 v[174:177], v194 offset:1024
	ds_read_b128 v[178:181], v194 offset:2048
	ds_read_b128 v[182:185], v194 offset:3072
	ds_read_b128 v[196:199], v194 offset:4096
	ds_read_b128 v[200:203], v194 offset:5120
	ds_read_b128 v[204:207], v194 offset:6144
	ds_read_b128 v[210:213], v194 offset:7168
	global_load_lds_dwordx4 v[186:187], off
	v_lshl_add_u64 v[186:187], s[26:27], 0, v[164:165]
	s_add_i32 m0, s1, 0xe000
	s_nop 0
	global_load_lds_dwordx4 v[186:187], off
	s_waitcnt vmcnt(8)
	s_waitcnt lgkmcnt(0)
	s_barrier
	s_setprio 1
	v_mfma_f32_16x16x32_bf16 v[124:127], v[128:131], v[170:173], 0
	v_mfma_f32_16x16x32_bf16 v[120:123], v[136:139], v[170:173], 0
	v_mfma_f32_16x16x32_bf16 v[108:111], v[128:131], v[178:181], 0
	v_mfma_f32_16x16x32_bf16 v[104:107], v[136:139], v[178:181], 0
	v_mfma_f32_16x16x32_bf16 v[92:95], v[128:131], v[196:199], 0
	v_mfma_f32_16x16x32_bf16 v[88:91], v[136:139], v[196:199], 0
	v_mfma_f32_16x16x32_bf16 v[76:79], v[128:131], v[204:207], 0
	v_mfma_f32_16x16x32_bf16 v[72:75], v[136:139], v[204:207], 0
	v_mfma_f32_16x16x32_bf16 v[124:127], v[132:135], v[174:177], v[124:127]
	v_mfma_f32_16x16x32_bf16 v[120:123], v[140:143], v[174:177], v[120:123]
	v_mfma_f32_16x16x32_bf16 v[108:111], v[132:135], v[182:185], v[108:111]
	v_mfma_f32_16x16x32_bf16 v[104:107], v[140:143], v[182:185], v[104:107]
	v_mfma_f32_16x16x32_bf16 v[92:95], v[132:135], v[200:203], v[92:95]
	v_mfma_f32_16x16x32_bf16 v[88:91], v[140:143], v[200:203], v[88:91]
	v_mfma_f32_16x16x32_bf16 v[76:79], v[132:135], v[210:213], v[76:79]
	v_mfma_f32_16x16x32_bf16 v[72:75], v[140:143], v[210:213], v[72:75]
	s_setprio 0
	s_setprio 1
	v_mfma_f32_16x16x32_bf16 v[116:119], v[144:147], v[170:173], 0
	v_mfma_f32_16x16x32_bf16 v[112:115], v[152:155], v[170:173], 0
	v_mfma_f32_16x16x32_bf16 v[100:103], v[144:147], v[178:181], 0
	v_mfma_f32_16x16x32_bf16 v[96:99], v[152:155], v[178:181], 0
	v_mfma_f32_16x16x32_bf16 v[84:87], v[144:147], v[196:199], 0
	v_mfma_f32_16x16x32_bf16 v[80:83], v[152:155], v[196:199], 0
	v_mfma_f32_16x16x32_bf16 v[68:71], v[144:147], v[204:207], 0
	v_mfma_f32_16x16x32_bf16 v[64:67], v[152:155], v[204:207], 0
	v_mfma_f32_16x16x32_bf16 v[116:119], v[148:151], v[174:177], v[116:119]
	v_mfma_f32_16x16x32_bf16 v[112:115], v[166:169], v[174:177], v[112:115]
	v_mfma_f32_16x16x32_bf16 v[100:103], v[148:151], v[182:185], v[100:103]
	v_mfma_f32_16x16x32_bf16 v[96:99], v[166:169], v[182:185], v[96:99]
	v_mfma_f32_16x16x32_bf16 v[84:87], v[148:151], v[200:203], v[84:87]
	v_mfma_f32_16x16x32_bf16 v[80:83], v[166:169], v[200:203], v[80:83]
	v_mfma_f32_16x16x32_bf16 v[68:71], v[148:151], v[210:213], v[68:71]
	v_mfma_f32_16x16x32_bf16 v[64:67], v[166:169], v[210:213], v[64:67]
	s_setprio 0
	s_barrier
	s_add_i32 s4, s4, s0
	v_lshl_add_u64 v[186:187], s[30:31], 0, v[156:157]
	s_mov_b32 m0, s4
	ds_read_b128 v[170:173], v194 offset:16384
	ds_read_b128 v[174:177], v194 offset:17408
	ds_read_b128 v[178:181], v194 offset:18432
	ds_read_b128 v[182:185], v194 offset:19456
	ds_read_b128 v[196:199], v194 offset:20480
	ds_read_b128 v[200:203], v194 offset:21504
	ds_read_b128 v[204:207], v194 offset:22528
	ds_read_b128 v[210:213], v194 offset:23552
	global_load_lds_dwordx4 v[186:187], off
	s_add_i32 m0, s4, 0x2000
	s_add_u32 s4, s30, s12
	v_lshl_add_u64 v[186:187], s[30:31], 0, v[158:159]
	s_addc_u32 s5, s31, s13
	s_add_i32 s41, s41, s0
	global_load_lds_dwordx4 v[186:187], off
	v_lshl_add_u64 v[186:187], s[4:5], 0, v[156:157]
	s_mov_b32 m0, s41
	s_nop 0
	global_load_lds_dwordx4 v[186:187], off
	v_lshl_add_u64 v[186:187], s[4:5], 0, v[158:159]
	s_add_i32 m0, s41, 0x2000
	s_nop 0
	global_load_lds_dwordx4 v[186:187], off
	v_lshl_add_u64 v[186:187], s[34:35], 0, v[156:157]
	s_mov_b32 m0, s1
	s_nop 0
	global_load_lds_dwordx4 v[186:187], off
	v_lshl_add_u64 v[186:187], s[34:35], 0, v[158:159]
	s_mov_b32 m0, s3
	s_nop 0
	global_load_lds_dwordx4 v[186:187], off
	s_waitcnt vmcnt(8)
	s_waitcnt lgkmcnt(0)
	s_barrier
; #define PG8_STAGE(bufoff, gbase, voff) do { _Pragma("unroll") for (int _i = 0; _i < 2; ++_i) \
;         __builtin_amdgcn_global_load_lds((const unsigned*)((const char*)(gbase) + (voff)[_i]), (PG8_LAS unsigned*)(lds + (bufoff) + ldsw + _i * 8192), 16, 0, 0); } while (0)
; #define PG8_LDA(dst, b, h) do { _Pragma("unroll") for (int m = 0; m < 4; ++m) _Pragma("unroll") for (int k = 0; k < 2; ++k) dst[m][k] = *(const PG8_LAS bf16x8*)(lds + PG8_SA(b, h) + aoff + m * 2048 + k * 1024); } while (0)
; #define PG8_LDB(dst, b, h) do { _Pragma("unroll") for (int n = 0; n < 2; ++n) _Pragma("unroll") for (int k = 0; k < 2; ++k) dst[n][k] = *(const PG8_LAS bf16x8*)(lds + PG8_SB(b, h) + boff + n * 2048 + k * 1024); } while (0)
; #define PG8_MMA(ai, bj, At, Bt) do { __builtin_amdgcn_s_setprio(1); _Pragma("unroll") for (int m = 0; m < 4; ++m) _Pragma("unroll") for (int n = 0; n < 2; ++n) _Pragma("unroll") for (int k = 0; k < 2; ++k) \
;         acc[ai][bj][m][n] = __builtin_amdgcn_mfma_f32_16x16x32_bf16(Bt[n][k], At[m][k], acc[ai][bj][m][n], 0, 0, 0); __builtin_amdgcn_s_setprio(0); } while (0)
; #define PG8_WAIT_V(n) asm volatile("s_waitcnt vmcnt(" #n ")" ::: "memory")
; #define PG8_WAIT_L(n) asm volatile("s_waitcnt lgkmcnt(" #n ")" ::: "memory")
; #define PG8_BAR __builtin_amdgcn_s_barrier()
; #define PG8_SCHED __builtin_amdgcn_sched_barrier(0)
; template <class Epi, class Sched, bool ALIGN_EPI = false, bool SP2 = false>
; __device__ __forceinline__ void gemm_phase(PG8_LAS unsigned char* lds, const Gemm g, const Sched& S, const Epi& E, const int tid_in) {
;     ...
;             PG8_WAIT_V(8); PG8_WAIT_L(0); PG8_BAR; PG8_MMA(1, 0, At, B0); PG8_MMA(1, 1, At, B1); PG8_BAR; PG8_SCHED;
;             PG8_LDB(B0, 1, 0); PG8_LDB(B1, 1, 1); PG8_SCHED; PG8_LDA(At, 1, 0); PG8_STAGE(PG8_SA(0, 1), a2 + hstepA, voffA);
;             PG8_WAIT_V(8); PG8_WAIT_L(0); PG8_BAR; PG8_MMA(0, 0, At, B0); PG8_MMA(0, 1, At, B1); PG8_BAR; PG8_SCHED;
	s_setprio 1
	v_mfma_f32_16x16x32_bf16 v[60:63], v[128:131], v[170:173], 0
	v_mfma_f32_16x16x32_bf16 v[56:59], v[136:139], v[170:173], 0
	v_mfma_f32_16x16x32_bf16 v[44:47], v[128:131], v[178:181], 0
	v_mfma_f32_16x16x32_bf16 v[40:43], v[136:139], v[178:181], 0
	v_mfma_f32_16x16x32_bf16 v[28:31], v[128:131], v[196:199], 0
	v_mfma_f32_16x16x32_bf16 v[24:27], v[136:139], v[196:199], 0
	v_mfma_f32_16x16x32_bf16 v[12:15], v[128:131], v[204:207], 0
	v_mfma_f32_16x16x32_bf16 v[8:11], v[136:139], v[204:207], 0
	v_mfma_f32_16x16x32_bf16 v[60:63], v[132:135], v[174:177], v[60:63]
	v_mfma_f32_16x16x32_bf16 v[56:59], v[140:143], v[174:177], v[56:59]
	v_mfma_f32_16x16x32_bf16 v[44:47], v[132:135], v[182:185], v[44:47]
	v_mfma_f32_16x16x32_bf16 v[40:43], v[140:143], v[182:185], v[40:43]
	v_mfma_f32_16x16x32_bf16 v[28:31], v[132:135], v[200:203], v[28:31]
	v_mfma_f32_16x16x32_bf16 v[24:27], v[140:143], v[200:203], v[24:27]
	v_mfma_f32_16x16x32_bf16 v[12:15], v[132:135], v[210:213], v[12:15]
	v_mfma_f32_16x16x32_bf16 v[8:11], v[140:143], v[210:213], v[8:11]
	s_setprio 0
	s_setprio 1
	v_mfma_f32_16x16x32_bf16 v[52:55], v[144:147], v[170:173], 0
	v_mfma_f32_16x16x32_bf16 v[48:51], v[152:155], v[170:173], 0
	v_mfma_f32_16x16x32_bf16 v[36:39], v[144:147], v[178:181], 0
	v_mfma_f32_16x16x32_bf16 v[32:35], v[152:155], v[178:181], 0
	v_mfma_f32_16x16x32_bf16 v[20:23], v[144:147], v[196:199], 0
	v_mfma_f32_16x16x32_bf16 v[16:19], v[152:155], v[196:199], 0
	v_mfma_f32_16x16x32_bf16 v[4:7], v[144:147], v[204:207], 0
	v_mfma_f32_16x16x32_bf16 v[0:3], v[152:155], v[204:207], 0
	v_mfma_f32_16x16x32_bf16 v[52:55], v[148:151], v[174:177], v[52:55]
	v_mfma_f32_16x16x32_bf16 v[48:51], v[166:169], v[174:177], v[48:51]
	v_mfma_f32_16x16x32_bf16 v[36:39], v[148:151], v[182:185], v[36:39]
	v_mfma_f32_16x16x32_bf16 v[32:35], v[166:169], v[182:185], v[32:35]
	v_mfma_f32_16x16x32_bf16 v[20:23], v[148:151], v[200:203], v[20:23]
	v_mfma_f32_16x16x32_bf16 v[16:19], v[166:169], v[200:203], v[16:19]
	v_mfma_f32_16x16x32_bf16 v[4:7], v[148:151], v[210:213], v[4:7]
	v_mfma_f32_16x16x32_bf16 v[0:3], v[166:169], v[210:213], v[0:3]
	s_setprio 0
	s_barrier
	s_add_i32 s41, 0, 0x18000
	s_add_i32 s64, 0, 0x1c000
	v_add_u32_e32 v140, s41, v190
	v_add_u32_e32 v166, s64, v190
	ds_read_b128 v[128:131], v140
	ds_read_b128 v[132:135], v140 offset:1024
	ds_read_b128 v[136:139], v140 offset:2048
	ds_read_b128 v[140:143], v140 offset:3072
	ds_read_b128 v[144:147], v166
	ds_read_b128 v[148:151], v166 offset:1024
	ds_read_b128 v[152:155], v166 offset:2048
	ds_read_b128 v[166:169], v166 offset:3072
	s_add_u32 s4, s34, s12
	s_addc_u32 s5, s35, s13
	s_mov_b32 m0, s11
	v_lshl_add_u64 v[186:187], s[4:5], 0, v[156:157]
	ds_read_b128 v[170:173], v194 offset:32768
	ds_read_b128 v[174:177], v194 offset:33792
	ds_read_b128 v[178:181], v194 offset:34816
	ds_read_b128 v[182:185], v194 offset:35840
	ds_read_b128 v[196:199], v194 offset:36864
	ds_read_b128 v[200:203], v194 offset:37888
	ds_read_b128 v[204:207], v194 offset:38912
	ds_read_b128 v[210:213], v194 offset:39936
	global_load_lds_dwordx4 v[186:187], off
	v_lshl_add_u64 v[186:187], s[4:5], 0, v[158:159]
	s_mov_b32 m0, s33
	s_nop 0
	global_load_lds_dwordx4 v[186:187], off
	s_waitcnt vmcnt(8)
	s_waitcnt lgkmcnt(0)
	s_barrier
	s_setprio 1
	v_mfma_f32_16x16x32_bf16 v[124:127], v[128:131], v[170:173], v[124:127]
	v_mfma_f32_16x16x32_bf16 v[120:123], v[136:139], v[170:173], v[120:123]
	v_mfma_f32_16x16x32_bf16 v[108:111], v[128:131], v[178:181], v[108:111]
	v_mfma_f32_16x16x32_bf16 v[104:107], v[136:139], v[178:181], v[104:107]
	v_mfma_f32_16x16x32_bf16 v[92:95], v[128:131], v[196:199], v[92:95]
	v_mfma_f32_16x16x32_bf16 v[88:91], v[136:139], v[196:199], v[88:91]
	v_mfma_f32_16x16x32_bf16 v[76:79], v[128:131], v[204:207], v[76:79]
	v_mfma_f32_16x16x32_bf16 v[72:75], v[136:139], v[204:207], v[72:75]
	v_mfma_f32_16x16x32_bf16 v[124:127], v[132:135], v[174:177], v[124:127]
	v_mfma_f32_16x16x32_bf16 v[120:123], v[140:143], v[174:177], v[120:123]
	v_mfma_f32_16x16x32_bf16 v[108:111], v[132:135], v[182:185], v[108:111]
	v_mfma_f32_16x16x32_bf16 v[104:107], v[140:143], v[182:185], v[104:107]
	v_mfma_f32_16x16x32_bf16 v[92:95], v[132:135], v[200:203], v[92:95]
	v_mfma_f32_16x16x32_bf16 v[88:91], v[140:143], v[200:203], v[88:91]
	v_mfma_f32_16x16x32_bf16 v[76:79], v[132:135], v[210:213], v[76:79]
	v_mfma_f32_16x16x32_bf16 v[72:75], v[140:143], v[210:213], v[72:75]
	s_setprio 0
	s_setprio 1
	v_mfma_f32_16x16x32_bf16 v[116:119], v[144:147], v[170:173], v[116:119]
	v_mfma_f32_16x16x32_bf16 v[112:115], v[152:155], v[170:173], v[112:115]
	v_mfma_f32_16x16x32_bf16 v[100:103], v[144:147], v[178:181], v[100:103]
	v_mfma_f32_16x16x32_bf16 v[96:99], v[152:155], v[178:181], v[96:99]
	v_mfma_f32_16x16x32_bf16 v[84:87], v[144:147], v[196:199], v[84:87]
	v_mfma_f32_16x16x32_bf16 v[80:83], v[152:155], v[196:199], v[80:83]
	v_mfma_f32_16x16x32_bf16 v[68:71], v[144:147], v[204:207], v[68:71]
	v_mfma_f32_16x16x32_bf16 v[64:67], v[152:155], v[204:207], v[64:67]
	v_mfma_f32_16x16x32_bf16 v[116:119], v[148:151], v[174:177], v[116:119]
	v_mfma_f32_16x16x32_bf16 v[112:115], v[166:169], v[174:177], v[112:115]
	v_mfma_f32_16x16x32_bf16 v[100:103], v[148:151], v[182:185], v[100:103]
	v_mfma_f32_16x16x32_bf16 v[96:99], v[166:169], v[182:185], v[96:99]
	v_mfma_f32_16x16x32_bf16 v[84:87], v[148:151], v[200:203], v[84:87]
	v_mfma_f32_16x16x32_bf16 v[80:83], v[166:169], v[200:203], v[80:83]
	v_mfma_f32_16x16x32_bf16 v[68:71], v[148:151], v[210:213], v[68:71]
	v_mfma_f32_16x16x32_bf16 v[64:67], v[166:169], v[210:213], v[64:67]
	s_setprio 0
	s_barrier
; #define PG8_STAGE(bufoff, gbase, voff) do { _Pragma("unroll") for (int _i = 0; _i < 2; ++_i) \
;         __builtin_amdgcn_global_load_lds((const unsigned*)((const char*)(gbase) + (voff)[_i]), (PG8_LAS unsigned*)(lds + (bufoff) + ldsw + _i * 8192), 16, 0, 0); } while (0)
; #define PG8_LDA(dst, b, h) do { _Pragma("unroll") for (int m = 0; m < 4; ++m) _Pragma("unroll") for (int k = 0; k < 2; ++k) dst[m][k] = *(const PG8_LAS bf16x8*)(lds + PG8_SA(b, h) + aoff + m * 2048 + k * 1024); } while (0)
; #define PG8_LDB(dst, b, h) do { _Pragma("unroll") for (int n = 0; n < 2; ++n) _Pragma("unroll") for (int k = 0; k < 2; ++k) dst[n][k] = *(const PG8_LAS bf16x8*)(lds + PG8_SB(b, h) + boff + n * 2048 + k * 1024); } while (0)
; #define PG8_MMA(ai, bj, At, Bt) do { __builtin_amdgcn_s_setprio(1); _Pragma("unroll") for (int m = 0; m < 4; ++m) _Pragma("unroll") for (int n = 0; n < 2; ++n) _Pragma("unroll") for (int k = 0; k < 2; ++k) \
;         acc[ai][bj][m][n] = __builtin_amdgcn_mfma_f32_16x16x32_bf16(Bt[n][k], At[m][k], acc[ai][bj][m][n], 0, 0, 0); __builtin_amdgcn_s_setprio(0); } while (0)
; #define PG8_WAIT_V(n) asm volatile("s_waitcnt vmcnt(" #n ")" ::: "memory")
; #define PG8_BAR __builtin_amdgcn_s_barrier()
; template <class Epi, class Sched, bool ALIGN_EPI = false, bool SP2 = false>
; __device__ __forceinline__ void gemm_phase(PG8_LAS unsigned char* lds, const Gemm g, const Sched& S, const Epi& E, const int tid_in) {
;     ...
;         for (int t = 0; t < nt; t += 2) {
;             const bool last = (t == nt - 2);
;             const char* a1 = cA + (size_t)(t + 1) * kstepA;
;             const char* a2 = last ? nA : cA + (size_t)(t + 2) * kstepA; const char* b2 = last ? nB : cB + (size_t)(t + 2) * kstepB;
;             const char* a3 = a2 + kstepA; const char* b3 = b2 + kstepB;
;             if (last && has_next) S.a_ready(nxt);
;             if constexpr (SP2) {
;             PG8_LDB(B0, 0, 0); PG8_LDB(B1, 0, 1); PG8_SCHED; PG8_LDA(At, 0, 0); PG8_STAGE(PG8_SA(1, 1), a1 + hstepA, voffA);
;             PG8_WAIT_V(8); PG8_WAIT_L(0); PG8_BAR; PG8_MMA(0, 0, At, B0); PG8_MMA(0, 1, At, B1); PG8_BAR; PG8_SCHED;
;     ...
;             PG8_LDA(At, 1, 1); PG8_STAGE(PG8_SB(1, 0), b3, voffB); PG8_STAGE(PG8_SB(1, 1), b3 + hstepB, voffB); PG8_STAGE(PG8_SA(1, 0), a3, voffA);
;             PG8_WAIT_V(8); PG8_WAIT_L(0); PG8_BAR; PG8_MMA(1, 0, At, B0); PG8_MMA(1, 1, At, B1); PG8_BAR; PG8_SCHED;
	s_add_u32 s4, s30, 0x4000
	s_addc_u32 s5, s31, 0
	s_add_i32 s30, s41, s0
	v_lshl_add_u64 v[186:187], s[4:5], 0, v[156:157]
	s_mov_b32 m0, s30
	ds_read_b128 v[170:173], v194 offset:49152
	ds_read_b128 v[174:177], v194 offset:50176
	ds_read_b128 v[178:181], v194 offset:51200
	ds_read_b128 v[182:185], v194 offset:52224
	ds_read_b128 v[196:199], v194 offset:53248
	ds_read_b128 v[200:203], v194 offset:54272
	ds_read_b128 v[204:207], v194 offset:55296
	ds_read_b128 v[210:213], v194 offset:56320
	global_load_lds_dwordx4 v[186:187], off
	s_add_i32 m0, s30, 0x2000
	v_lshl_add_u64 v[186:187], s[4:5], 0, v[158:159]
	s_add_u32 s4, s4, s12
	s_addc_u32 s5, s5, s13
	s_add_i32 s30, s64, s0
	global_load_lds_dwordx4 v[186:187], off
	v_lshl_add_u64 v[186:187], s[4:5], 0, v[156:157]
	s_mov_b32 m0, s30
	s_nop 0
	global_load_lds_dwordx4 v[186:187], off
	v_lshl_add_u64 v[186:187], s[4:5], 0, v[158:159]
	s_add_i32 m0, s30, 0x2000
	s_nop 0
	global_load_lds_dwordx4 v[186:187], off
	v_lshl_add_u64 v[186:187], s[28:29], 0, v[156:157]
	s_mov_b32 m0, s37
	s_nop 0
	global_load_lds_dwordx4 v[186:187], off
	v_lshl_add_u64 v[186:187], s[28:29], 0, v[158:159]
	s_mov_b32 m0, s42
	s_nop 0
	global_load_lds_dwordx4 v[186:187], off
	s_waitcnt vmcnt(8)
	s_waitcnt lgkmcnt(0)
	s_barrier
	s_setprio 1
	v_mfma_f32_16x16x32_bf16 v[60:63], v[128:131], v[170:173], v[60:63]
	v_mfma_f32_16x16x32_bf16 v[56:59], v[136:139], v[170:173], v[56:59]
	v_mfma_f32_16x16x32_bf16 v[44:47], v[128:131], v[178:181], v[44:47]
	v_mfma_f32_16x16x32_bf16 v[40:43], v[136:139], v[178:181], v[40:43]
	v_mfma_f32_16x16x32_bf16 v[28:31], v[128:131], v[196:199], v[28:31]
	v_mfma_f32_16x16x32_bf16 v[24:27], v[136:139], v[196:199], v[24:27]
	v_mfma_f32_16x16x32_bf16 v[12:15], v[128:131], v[204:207], v[12:15]
	v_mfma_f32_16x16x32_bf16 v[8:11], v[136:139], v[204:207], v[8:11]
	v_mfma_f32_16x16x32_bf16 v[60:63], v[132:135], v[174:177], v[60:63]
	v_mfma_f32_16x16x32_bf16 v[56:59], v[140:143], v[174:177], v[56:59]
	v_mfma_f32_16x16x32_bf16 v[44:47], v[132:135], v[182:185], v[44:47]
	v_mfma_f32_16x16x32_bf16 v[40:43], v[140:143], v[182:185], v[40:43]
	v_mfma_f32_16x16x32_bf16 v[28:31], v[132:135], v[200:203], v[28:31]
	v_mfma_f32_16x16x32_bf16 v[24:27], v[140:143], v[200:203], v[24:27]
	v_mfma_f32_16x16x32_bf16 v[12:15], v[132:135], v[210:213], v[12:15]
	v_mfma_f32_16x16x32_bf16 v[8:11], v[140:143], v[210:213], v[8:11]
	s_setprio 0
	s_setprio 1
	v_mfma_f32_16x16x32_bf16 v[52:55], v[144:147], v[170:173], v[52:55]
	v_mfma_f32_16x16x32_bf16 v[48:51], v[152:155], v[170:173], v[48:51]
	v_mfma_f32_16x16x32_bf16 v[36:39], v[144:147], v[178:181], v[36:39]
	v_mfma_f32_16x16x32_bf16 v[32:35], v[152:155], v[178:181], v[32:35]
	v_mfma_f32_16x16x32_bf16 v[20:23], v[144:147], v[196:199], v[20:23]
	v_mfma_f32_16x16x32_bf16 v[16:19], v[152:155], v[196:199], v[16:19]
	v_mfma_f32_16x16x32_bf16 v[4:7], v[144:147], v[204:207], v[4:7]
	v_mfma_f32_16x16x32_bf16 v[0:3], v[152:155], v[204:207], v[0:3]
	v_mfma_f32_16x16x32_bf16 v[52:55], v[148:151], v[174:177], v[52:55]
	v_mfma_f32_16x16x32_bf16 v[48:51], v[166:169], v[174:177], v[48:51]
	v_mfma_f32_16x16x32_bf16 v[36:39], v[148:151], v[182:185], v[36:39]
	v_mfma_f32_16x16x32_bf16 v[32:35], v[166:169], v[182:185], v[32:35]
	v_mfma_f32_16x16x32_bf16 v[20:23], v[148:151], v[200:203], v[20:23]
	v_mfma_f32_16x16x32_bf16 v[16:19], v[166:169], v[200:203], v[16:19]
	v_mfma_f32_16x16x32_bf16 v[4:7], v[148:151], v[210:213], v[4:7]
	v_mfma_f32_16x16x32_bf16 v[0:3], v[166:169], v[210:213], v[0:3]
	s_setprio 0
	s_barrier
	s_add_u32 s26, s26, 0x8000
	s_addc_u32 s27, s27, 0
	s_add_u32 s6, s6, 0x8000
	s_addc_u32 s7, s7, 0
	s_cmp_ge_i32 s40, s10
	s_mov_b32 s28, s40
	s_cbranch_scc1 .LBB0_146
.LBB0_145:
	s_add_i32 s40, s28, 2
	s_add_u32 s4, s26, 0x4000
	s_addc_u32 s5, s27, 0
	s_cmp_eq_u32 s43, s28
	s_cselect_b32 s34, s22, s4
	s_cselect_b32 s35, s23, s5
	s_cselect_b32 s30, s24, s6
	s_cselect_b32 s31, s25, s7
	s_add_u32 s28, s34, 0x4000
	s_addc_u32 s29, s35, 0
	s_add_i32 s4, 0, 0x10000
	s_add_i32 s41, 0, 0x14000
	v_add_u32_e32 v140, s4, v190
	v_add_u32_e32 v166, s41, v190
	ds_read_b128 v[128:131], v140
	ds_read_b128 v[132:135], v140 offset:1024
	ds_read_b128 v[136:139], v140 offset:2048
	ds_read_b128 v[140:143], v140 offset:3072
	ds_read_b128 v[144:147], v166
	ds_read_b128 v[148:151], v166 offset:1024
	ds_read_b128 v[152:155], v166 offset:2048
	ds_read_b128 v[166:169], v166 offset:3072
	v_lshl_add_u64 v[186:187], s[26:27], 0, v[162:163]
	s_add_i32 m0, s1, 0xc000
	ds_read_b128 v[170:173], v194
	ds_read_b128 v[174:177], v194 offset:1024
	ds_read_b128 v[178:181], v194 offset:2048
	ds_read_b128 v[182:185], v194 offset:3072
	ds_read_b128 v[196:199], v194 offset:4096
	ds_read_b128 v[200:203], v194 offset:5120
	ds_read_b128 v[204:207], v194 offset:6144
	ds_read_b128 v[210:213], v194 offset:7168
	global_load_lds_dwordx4 v[186:187], off
	v_lshl_add_u64 v[186:187], s[26:27], 0, v[164:165]
	s_add_i32 m0, s1, 0xe000
	s_nop 0
	global_load_lds_dwordx4 v[186:187], off
	s_waitcnt vmcnt(8)
	s_waitcnt lgkmcnt(0)
	s_barrier
; #define PG8_STAGE(bufoff, gbase, voff) do { _Pragma("unroll") for (int _i = 0; _i < 2; ++_i) \
;         __builtin_amdgcn_global_load_lds((const unsigned*)((const char*)(gbase) + (voff)[_i]), (PG8_LAS unsigned*)(lds + (bufoff) + ldsw + _i * 8192), 16, 0, 0); } while (0)
; #define PG8_LDA(dst, b, h) do { _Pragma("unroll") for (int m = 0; m < 4; ++m) _Pragma("unroll") for (int k = 0; k < 2; ++k) dst[m][k] = *(const PG8_LAS bf16x8*)(lds + PG8_SA(b, h) + aoff + m * 2048 + k * 1024); } while (0)
; #define PG8_MMA(ai, bj, At, Bt) do { __builtin_amdgcn_s_setprio(1); _Pragma("unroll") for (int m = 0; m < 4; ++m) _Pragma("unroll") for (int n = 0; n < 2; ++n) _Pragma("unroll") for (int k = 0; k < 2; ++k) \
;         acc[ai][bj][m][n] = __builtin_amdgcn_mfma_f32_16x16x32_bf16(Bt[n][k], At[m][k], acc[ai][bj][m][n], 0, 0, 0); __builtin_amdgcn_s_setprio(0); } while (0)
; #define PG8_WAIT_V(n) asm volatile("s_waitcnt vmcnt(" #n ")" ::: "memory")
; #define PG8_WAIT_L(n) asm volatile("s_waitcnt lgkmcnt(" #n ")" ::: "memory")
; #define PG8_BAR __builtin_amdgcn_s_barrier()
; #define PG8_SCHED __builtin_amdgcn_sched_barrier(0)
; template <class Epi, class Sched, bool ALIGN_EPI = false, bool SP2 = false>
; __device__ __forceinline__ void gemm_phase(PG8_LAS unsigned char* lds, const Gemm g, const Sched& S, const Epi& E, const int tid_in) {
;     ...
;             PG8_WAIT_V(8); PG8_WAIT_L(0); PG8_BAR; PG8_MMA(0, 0, At, B0); PG8_MMA(0, 1, At, B1); PG8_BAR; PG8_SCHED;
;             PG8_LDA(At, 0, 1); PG8_STAGE(PG8_SB(0, 0), b2, voffB); PG8_STAGE(PG8_SB(0, 1), b2 + hstepB, voffB); PG8_STAGE(PG8_SA(0, 0), a2, voffA);
;             PG8_WAIT_V(8); PG8_WAIT_L(0); PG8_BAR; PG8_MMA(1, 0, At, B0); PG8_MMA(1, 1, At, B1); PG8_BAR; PG8_SCHED;
	s_setprio 1
	v_mfma_f32_16x16x32_bf16 v[124:127], v[128:131], v[170:173], v[124:127]
	v_mfma_f32_16x16x32_bf16 v[120:123], v[136:139], v[170:173], v[120:123]
	v_mfma_f32_16x16x32_bf16 v[108:111], v[128:131], v[178:181], v[108:111]
	v_mfma_f32_16x16x32_bf16 v[104:107], v[136:139], v[178:181], v[104:107]
	v_mfma_f32_16x16x32_bf16 v[92:95], v[128:131], v[196:199], v[92:95]
	v_mfma_f32_16x16x32_bf16 v[88:91], v[136:139], v[196:199], v[88:91]
	v_mfma_f32_16x16x32_bf16 v[76:79], v[128:131], v[204:207], v[76:79]
	v_mfma_f32_16x16x32_bf16 v[72:75], v[136:139], v[204:207], v[72:75]
	v_mfma_f32_16x16x32_bf16 v[124:127], v[132:135], v[174:177], v[124:127]
	v_mfma_f32_16x16x32_bf16 v[120:123], v[140:143], v[174:177], v[120:123]
	v_mfma_f32_16x16x32_bf16 v[108:111], v[132:135], v[182:185], v[108:111]
	v_mfma_f32_16x16x32_bf16 v[104:107], v[140:143], v[182:185], v[104:107]
	v_mfma_f32_16x16x32_bf16 v[92:95], v[132:135], v[200:203], v[92:95]
	v_mfma_f32_16x16x32_bf16 v[88:91], v[140:143], v[200:203], v[88:91]
	v_mfma_f32_16x16x32_bf16 v[76:79], v[132:135], v[210:213], v[76:79]
	v_mfma_f32_16x16x32_bf16 v[72:75], v[140:143], v[210:213], v[72:75]
	s_setprio 0
	s_setprio 1
	v_mfma_f32_16x16x32_bf16 v[116:119], v[144:147], v[170:173], v[116:119]
	v_mfma_f32_16x16x32_bf16 v[112:115], v[152:155], v[170:173], v[112:115]
	v_mfma_f32_16x16x32_bf16 v[100:103], v[144:147], v[178:181], v[100:103]
	v_mfma_f32_16x16x32_bf16 v[96:99], v[152:155], v[178:181], v[96:99]
	v_mfma_f32_16x16x32_bf16 v[84:87], v[144:147], v[196:199], v[84:87]
	v_mfma_f32_16x16x32_bf16 v[80:83], v[152:155], v[196:199], v[80:83]
	v_mfma_f32_16x16x32_bf16 v[68:71], v[144:147], v[204:207], v[68:71]
	v_mfma_f32_16x16x32_bf16 v[64:67], v[152:155], v[204:207], v[64:67]
	v_mfma_f32_16x16x32_bf16 v[116:119], v[148:151], v[174:177], v[116:119]
	v_mfma_f32_16x16x32_bf16 v[112:115], v[166:169], v[174:177], v[112:115]
	v_mfma_f32_16x16x32_bf16 v[100:103], v[148:151], v[182:185], v[100:103]
	v_mfma_f32_16x16x32_bf16 v[96:99], v[166:169], v[182:185], v[96:99]
	v_mfma_f32_16x16x32_bf16 v[84:87], v[148:151], v[200:203], v[84:87]
	v_mfma_f32_16x16x32_bf16 v[80:83], v[166:169], v[200:203], v[80:83]
	v_mfma_f32_16x16x32_bf16 v[68:71], v[148:151], v[210:213], v[68:71]
	v_mfma_f32_16x16x32_bf16 v[64:67], v[166:169], v[210:213], v[64:67]
	s_setprio 0
	s_barrier
	s_add_i32 s4, s4, s0
	v_lshl_add_u64 v[186:187], s[30:31], 0, v[156:157]
	s_mov_b32 m0, s4
	ds_read_b128 v[170:173], v194 offset:16384
	ds_read_b128 v[174:177], v194 offset:17408
	ds_read_b128 v[178:181], v194 offset:18432
	ds_read_b128 v[182:185], v194 offset:19456
	ds_read_b128 v[196:199], v194 offset:20480
	ds_read_b128 v[200:203], v194 offset:21504
	ds_read_b128 v[204:207], v194 offset:22528
	ds_read_b128 v[210:213], v194 offset:23552
	global_load_lds_dwordx4 v[186:187], off
	s_add_i32 m0, s4, 0x2000
	s_add_u32 s4, s30, s12
	v_lshl_add_u64 v[186:187], s[30:31], 0, v[158:159]
	s_addc_u32 s5, s31, s13
	s_add_i32 s41, s41, s0
	global_load_lds_dwordx4 v[186:187], off
	v_lshl_add_u64 v[186:187], s[4:5], 0, v[156:157]
	s_mov_b32 m0, s41
	s_nop 0
	global_load_lds_dwordx4 v[186:187], off
	v_lshl_add_u64 v[186:187], s[4:5], 0, v[158:159]
	s_add_i32 m0, s41, 0x2000
	s_nop 0
	global_load_lds_dwordx4 v[186:187], off
	v_lshl_add_u64 v[186:187], s[34:35], 0, v[156:157]
	s_mov_b32 m0, s1
	s_nop 0
	global_load_lds_dwordx4 v[186:187], off
	v_lshl_add_u64 v[186:187], s[34:35], 0, v[158:159]
	s_mov_b32 m0, s3
	s_nop 0
	global_load_lds_dwordx4 v[186:187], off
	s_waitcnt vmcnt(8)
	s_waitcnt lgkmcnt(0)
	s_barrier
	s_setprio 1
	v_mfma_f32_16x16x32_bf16 v[60:63], v[128:131], v[170:173], v[60:63]
	v_mfma_f32_16x16x32_bf16 v[56:59], v[136:139], v[170:173], v[56:59]
	v_mfma_f32_16x16x32_bf16 v[44:47], v[128:131], v[178:181], v[44:47]
	v_mfma_f32_16x16x32_bf16 v[40:43], v[136:139], v[178:181], v[40:43]
	v_mfma_f32_16x16x32_bf16 v[28:31], v[128:131], v[196:199], v[28:31]
	v_mfma_f32_16x16x32_bf16 v[24:27], v[136:139], v[196:199], v[24:27]
	v_mfma_f32_16x16x32_bf16 v[12:15], v[128:131], v[204:207], v[12:15]
	v_mfma_f32_16x16x32_bf16 v[8:11], v[136:139], v[204:207], v[8:11]
	v_mfma_f32_16x16x32_bf16 v[60:63], v[132:135], v[174:177], v[60:63]
	v_mfma_f32_16x16x32_bf16 v[56:59], v[140:143], v[174:177], v[56:59]
	v_mfma_f32_16x16x32_bf16 v[44:47], v[132:135], v[182:185], v[44:47]
	v_mfma_f32_16x16x32_bf16 v[40:43], v[140:143], v[182:185], v[40:43]
	v_mfma_f32_16x16x32_bf16 v[28:31], v[132:135], v[200:203], v[28:31]
	v_mfma_f32_16x16x32_bf16 v[24:27], v[140:143], v[200:203], v[24:27]
	v_mfma_f32_16x16x32_bf16 v[12:15], v[132:135], v[210:213], v[12:15]
	v_mfma_f32_16x16x32_bf16 v[8:11], v[140:143], v[210:213], v[8:11]
	s_setprio 0
	s_setprio 1
	v_mfma_f32_16x16x32_bf16 v[52:55], v[144:147], v[170:173], v[52:55]
	v_mfma_f32_16x16x32_bf16 v[48:51], v[152:155], v[170:173], v[48:51]
	v_mfma_f32_16x16x32_bf16 v[36:39], v[144:147], v[178:181], v[36:39]
	v_mfma_f32_16x16x32_bf16 v[32:35], v[152:155], v[178:181], v[32:35]
	v_mfma_f32_16x16x32_bf16 v[20:23], v[144:147], v[196:199], v[20:23]
	v_mfma_f32_16x16x32_bf16 v[16:19], v[152:155], v[196:199], v[16:19]
	v_mfma_f32_16x16x32_bf16 v[4:7], v[144:147], v[204:207], v[4:7]
	v_mfma_f32_16x16x32_bf16 v[0:3], v[152:155], v[204:207], v[0:3]
	v_mfma_f32_16x16x32_bf16 v[52:55], v[148:151], v[174:177], v[52:55]
	v_mfma_f32_16x16x32_bf16 v[48:51], v[166:169], v[174:177], v[48:51]
	v_mfma_f32_16x16x32_bf16 v[36:39], v[148:151], v[182:185], v[36:39]
	v_mfma_f32_16x16x32_bf16 v[32:35], v[166:169], v[182:185], v[32:35]
	v_mfma_f32_16x16x32_bf16 v[20:23], v[148:151], v[200:203], v[20:23]
	v_mfma_f32_16x16x32_bf16 v[16:19], v[166:169], v[200:203], v[16:19]
	v_mfma_f32_16x16x32_bf16 v[4:7], v[148:151], v[210:213], v[4:7]
	v_mfma_f32_16x16x32_bf16 v[0:3], v[166:169], v[210:213], v[0:3]
	s_setprio 0
	s_barrier
; #define PG8_STAGE(bufoff, gbase, voff) do { _Pragma("unroll") for (int _i = 0; _i < 2; ++_i) \
;         __builtin_amdgcn_global_load_lds((const unsigned*)((const char*)(gbase) + (voff)[_i]), (PG8_LAS unsigned*)(lds + (bufoff) + ldsw + _i * 8192), 16, 0, 0); } while (0)
; #define PG8_LDA(dst, b, h) do { _Pragma("unroll") for (int m = 0; m < 4; ++m) _Pragma("unroll") for (int k = 0; k < 2; ++k) dst[m][k] = *(const PG8_LAS bf16x8*)(lds + PG8_SA(b, h) + aoff + m * 2048 + k * 1024); } while (0)
; #define PG8_LDB(dst, b, h) do { _Pragma("unroll") for (int n = 0; n < 2; ++n) _Pragma("unroll") for (int k = 0; k < 2; ++k) dst[n][k] = *(const PG8_LAS bf16x8*)(lds + PG8_SB(b, h) + boff + n * 2048 + k * 1024); } while (0)
; #define PG8_MMA(ai, bj, At, Bt) do { __builtin_amdgcn_s_setprio(1); _Pragma("unroll") for (int m = 0; m < 4; ++m) _Pragma("unroll") for (int n = 0; n < 2; ++n) _Pragma("unroll") for (int k = 0; k < 2; ++k) \
;         acc[ai][bj][m][n] = __builtin_amdgcn_mfma_f32_16x16x32_bf16(Bt[n][k], At[m][k], acc[ai][bj][m][n], 0, 0, 0); __builtin_amdgcn_s_setprio(0); } while (0)
; #define PG8_WAIT_V(n) asm volatile("s_waitcnt vmcnt(" #n ")" ::: "memory")
; #define PG8_WAIT_L(n) asm volatile("s_waitcnt lgkmcnt(" #n ")" ::: "memory")
; #define PG8_BAR __builtin_amdgcn_s_barrier()
; #define PG8_SCHED __builtin_amdgcn_sched_barrier(0)
; template <class Epi, class Sched, bool ALIGN_EPI = false, bool SP2 = false>
; __device__ __forceinline__ void gemm_phase(PG8_LAS unsigned char* lds, const Gemm g, const Sched& S, const Epi& E, const int tid_in) {
;     ...
;             PG8_LDB(B0, 1, 0); PG8_LDB(B1, 1, 1); PG8_SCHED; PG8_LDA(At, 1, 0); PG8_STAGE(PG8_SA(0, 1), a2 + hstepA, voffA);
;             PG8_WAIT_V(8); PG8_WAIT_L(0); PG8_BAR; PG8_MMA(0, 0, At, B0); PG8_MMA(0, 1, At, B1); PG8_BAR; PG8_SCHED;
	s_add_i32 s41, 0, 0x18000
	s_add_i32 s64, 0, 0x1c000
	v_add_u32_e32 v140, s41, v190
	v_add_u32_e32 v166, s64, v190
	ds_read_b128 v[128:131], v140
	ds_read_b128 v[132:135], v140 offset:1024
	ds_read_b128 v[136:139], v140 offset:2048
	ds_read_b128 v[140:143], v140 offset:3072
	ds_read_b128 v[144:147], v166
	ds_read_b128 v[148:151], v166 offset:1024
	ds_read_b128 v[152:155], v166 offset:2048
	ds_read_b128 v[166:169], v166 offset:3072
	s_add_u32 s4, s34, s12
	s_addc_u32 s5, s35, s13
	s_mov_b32 m0, s11
	v_lshl_add_u64 v[186:187], s[4:5], 0, v[156:157]
	ds_read_b128 v[170:173], v194 offset:32768
	ds_read_b128 v[174:177], v194 offset:33792
	ds_read_b128 v[178:181], v194 offset:34816
	ds_read_b128 v[182:185], v194 offset:35840
	ds_read_b128 v[196:199], v194 offset:36864
	ds_read_b128 v[200:203], v194 offset:37888
	ds_read_b128 v[204:207], v194 offset:38912
	ds_read_b128 v[210:213], v194 offset:39936
	global_load_lds_dwordx4 v[186:187], off
	v_lshl_add_u64 v[186:187], s[4:5], 0, v[158:159]
	s_mov_b32 m0, s33
	s_nop 0
	global_load_lds_dwordx4 v[186:187], off
	s_waitcnt vmcnt(8)
	s_waitcnt lgkmcnt(0)
	s_barrier
	s_setprio 1
	v_mfma_f32_16x16x32_bf16 v[124:127], v[128:131], v[170:173], v[124:127]
	v_mfma_f32_16x16x32_bf16 v[120:123], v[136:139], v[170:173], v[120:123]
	v_mfma_f32_16x16x32_bf16 v[108:111], v[128:131], v[178:181], v[108:111]
	v_mfma_f32_16x16x32_bf16 v[104:107], v[136:139], v[178:181], v[104:107]
	v_mfma_f32_16x16x32_bf16 v[92:95], v[128:131], v[196:199], v[92:95]
	v_mfma_f32_16x16x32_bf16 v[88:91], v[136:139], v[196:199], v[88:91]
	v_mfma_f32_16x16x32_bf16 v[76:79], v[128:131], v[204:207], v[76:79]
	v_mfma_f32_16x16x32_bf16 v[72:75], v[136:139], v[204:207], v[72:75]
	v_mfma_f32_16x16x32_bf16 v[124:127], v[132:135], v[174:177], v[124:127]
	v_mfma_f32_16x16x32_bf16 v[120:123], v[140:143], v[174:177], v[120:123]
	v_mfma_f32_16x16x32_bf16 v[108:111], v[132:135], v[182:185], v[108:111]
	v_mfma_f32_16x16x32_bf16 v[104:107], v[140:143], v[182:185], v[104:107]
	v_mfma_f32_16x16x32_bf16 v[92:95], v[132:135], v[200:203], v[92:95]
	v_mfma_f32_16x16x32_bf16 v[88:91], v[140:143], v[200:203], v[88:91]
	v_mfma_f32_16x16x32_bf16 v[76:79], v[132:135], v[210:213], v[76:79]
	v_mfma_f32_16x16x32_bf16 v[72:75], v[140:143], v[210:213], v[72:75]
	s_setprio 0
	s_setprio 1
	v_mfma_f32_16x16x32_bf16 v[116:119], v[144:147], v[170:173], v[116:119]
	v_mfma_f32_16x16x32_bf16 v[112:115], v[152:155], v[170:173], v[112:115]
	v_mfma_f32_16x16x32_bf16 v[100:103], v[144:147], v[178:181], v[100:103]
	v_mfma_f32_16x16x32_bf16 v[96:99], v[152:155], v[178:181], v[96:99]
	v_mfma_f32_16x16x32_bf16 v[84:87], v[144:147], v[196:199], v[84:87]
	v_mfma_f32_16x16x32_bf16 v[80:83], v[152:155], v[196:199], v[80:83]
	v_mfma_f32_16x16x32_bf16 v[68:71], v[144:147], v[204:207], v[68:71]
	v_mfma_f32_16x16x32_bf16 v[64:67], v[152:155], v[204:207], v[64:67]
	v_mfma_f32_16x16x32_bf16 v[116:119], v[148:151], v[174:177], v[116:119]
	v_mfma_f32_16x16x32_bf16 v[112:115], v[166:169], v[174:177], v[112:115]
	v_mfma_f32_16x16x32_bf16 v[100:103], v[148:151], v[182:185], v[100:103]
	v_mfma_f32_16x16x32_bf16 v[96:99], v[166:169], v[182:185], v[96:99]
	v_mfma_f32_16x16x32_bf16 v[84:87], v[148:151], v[200:203], v[84:87]
	v_mfma_f32_16x16x32_bf16 v[80:83], v[166:169], v[200:203], v[80:83]
	v_mfma_f32_16x16x32_bf16 v[68:71], v[148:151], v[210:213], v[68:71]
	v_mfma_f32_16x16x32_bf16 v[64:67], v[166:169], v[210:213], v[64:67]
	s_setprio 0
	s_barrier
; #define PG8_STAGE(bufoff, gbase, voff) do { _Pragma("unroll") for (int _i = 0; _i < 2; ++_i) \
;         __builtin_amdgcn_global_load_lds((const unsigned*)((const char*)(gbase) + (voff)[_i]), (PG8_LAS unsigned*)(lds + (bufoff) + ldsw + _i * 8192), 16, 0, 0); } while (0)
; #define PG8_LDA(dst, b, h) do { _Pragma("unroll") for (int m = 0; m < 4; ++m) _Pragma("unroll") for (int k = 0; k < 2; ++k) dst[m][k] = *(const PG8_LAS bf16x8*)(lds + PG8_SA(b, h) + aoff + m * 2048 + k * 1024); } while (0)
; #define PG8_MMA(ai, bj, At, Bt) do { __builtin_amdgcn_s_setprio(1); _Pragma("unroll") for (int m = 0; m < 4; ++m) _Pragma("unroll") for (int n = 0; n < 2; ++n) _Pragma("unroll") for (int k = 0; k < 2; ++k) \
;         acc[ai][bj][m][n] = __builtin_amdgcn_mfma_f32_16x16x32_bf16(Bt[n][k], At[m][k], acc[ai][bj][m][n], 0, 0, 0); __builtin_amdgcn_s_setprio(0); } while (0)
; #define PG8_WAIT_V(n) asm volatile("s_waitcnt vmcnt(" #n ")" ::: "memory")
; #define PG8_WAIT_L(n) asm volatile("s_waitcnt lgkmcnt(" #n ")" ::: "memory")
; #define PG8_BAR __builtin_amdgcn_s_barrier()
; #define PG8_SCHED __builtin_amdgcn_sched_barrier(0)
; template <class Epi, class Sched, bool ALIGN_EPI = false, bool SP2 = false>
; __device__ __forceinline__ void gemm_phase(PG8_LAS unsigned char* lds, const Gemm g, const Sched& S, const Epi& E, const int tid_in) {
;     ...
;         for (int t = 0; t < nt; t += 2) {
;     ...
;             PG8_LDA(At, 1, 1); PG8_STAGE(PG8_SB(1, 0), b3, voffB); PG8_STAGE(PG8_SB(1, 1), b3 + hstepB, voffB); PG8_STAGE(PG8_SA(1, 0), a3, voffA);
;             PG8_WAIT_V(8); PG8_WAIT_L(0); PG8_BAR; PG8_MMA(1, 0, At, B0); PG8_MMA(1, 1, At, B1); PG8_BAR; PG8_SCHED;
	s_add_u32 s4, s30, 0x4000
	s_addc_u32 s5, s31, 0
	s_add_i32 s30, s41, s0
	v_lshl_add_u64 v[186:187], s[4:5], 0, v[156:157]
	s_mov_b32 m0, s30
	ds_read_b128 v[170:173], v194 offset:49152
	ds_read_b128 v[174:177], v194 offset:50176
	ds_read_b128 v[178:181], v194 offset:51200
	ds_read_b128 v[182:185], v194 offset:52224
	ds_read_b128 v[196:199], v194 offset:53248
	ds_read_b128 v[200:203], v194 offset:54272
	ds_read_b128 v[204:207], v194 offset:55296
	ds_read_b128 v[210:213], v194 offset:56320
	global_load_lds_dwordx4 v[186:187], off
	s_add_i32 m0, s30, 0x2000
	v_lshl_add_u64 v[186:187], s[4:5], 0, v[158:159]
	s_add_u32 s4, s4, s12
	s_addc_u32 s5, s5, s13
	s_add_i32 s30, s64, s0
	global_load_lds_dwordx4 v[186:187], off
	v_lshl_add_u64 v[186:187], s[4:5], 0, v[156:157]
	s_mov_b32 m0, s30
	s_nop 0
	global_load_lds_dwordx4 v[186:187], off
	v_lshl_add_u64 v[186:187], s[4:5], 0, v[158:159]
	s_add_i32 m0, s30, 0x2000
	s_nop 0
	global_load_lds_dwordx4 v[186:187], off
	v_lshl_add_u64 v[186:187], s[28:29], 0, v[156:157]
	s_mov_b32 m0, s37
	s_nop 0
	global_load_lds_dwordx4 v[186:187], off
	v_lshl_add_u64 v[186:187], s[28:29], 0, v[158:159]
	s_mov_b32 m0, s42
	s_nop 0
	global_load_lds_dwordx4 v[186:187], off
	s_waitcnt vmcnt(8)
	s_waitcnt lgkmcnt(0)
	s_barrier
	s_setprio 1
	v_mfma_f32_16x16x32_bf16 v[60:63], v[128:131], v[170:173], v[60:63]
	v_mfma_f32_16x16x32_bf16 v[56:59], v[136:139], v[170:173], v[56:59]
	v_mfma_f32_16x16x32_bf16 v[44:47], v[128:131], v[178:181], v[44:47]
	v_mfma_f32_16x16x32_bf16 v[40:43], v[136:139], v[178:181], v[40:43]
	v_mfma_f32_16x16x32_bf16 v[28:31], v[128:131], v[196:199], v[28:31]
	v_mfma_f32_16x16x32_bf16 v[24:27], v[136:139], v[196:199], v[24:27]
	v_mfma_f32_16x16x32_bf16 v[12:15], v[128:131], v[204:207], v[12:15]
	v_mfma_f32_16x16x32_bf16 v[8:11], v[136:139], v[204:207], v[8:11]
	v_mfma_f32_16x16x32_bf16 v[60:63], v[132:135], v[174:177], v[60:63]
	v_mfma_f32_16x16x32_bf16 v[56:59], v[140:143], v[174:177], v[56:59]
	v_mfma_f32_16x16x32_bf16 v[44:47], v[132:135], v[182:185], v[44:47]
	v_mfma_f32_16x16x32_bf16 v[40:43], v[140:143], v[182:185], v[40:43]
	v_mfma_f32_16x16x32_bf16 v[28:31], v[132:135], v[200:203], v[28:31]
	v_mfma_f32_16x16x32_bf16 v[24:27], v[140:143], v[200:203], v[24:27]
	v_mfma_f32_16x16x32_bf16 v[12:15], v[132:135], v[210:213], v[12:15]
	v_mfma_f32_16x16x32_bf16 v[8:11], v[140:143], v[210:213], v[8:11]
	s_setprio 0
	s_setprio 1
	v_mfma_f32_16x16x32_bf16 v[52:55], v[144:147], v[170:173], v[52:55]
	v_mfma_f32_16x16x32_bf16 v[48:51], v[152:155], v[170:173], v[48:51]
	v_mfma_f32_16x16x32_bf16 v[36:39], v[144:147], v[178:181], v[36:39]
	v_mfma_f32_16x16x32_bf16 v[32:35], v[152:155], v[178:181], v[32:35]
	v_mfma_f32_16x16x32_bf16 v[20:23], v[144:147], v[196:199], v[20:23]
	v_mfma_f32_16x16x32_bf16 v[16:19], v[152:155], v[196:199], v[16:19]
	v_mfma_f32_16x16x32_bf16 v[4:7], v[144:147], v[204:207], v[4:7]
	v_mfma_f32_16x16x32_bf16 v[0:3], v[152:155], v[204:207], v[0:3]
	v_mfma_f32_16x16x32_bf16 v[52:55], v[148:151], v[174:177], v[52:55]
	v_mfma_f32_16x16x32_bf16 v[48:51], v[166:169], v[174:177], v[48:51]
	v_mfma_f32_16x16x32_bf16 v[36:39], v[148:151], v[182:185], v[36:39]
	v_mfma_f32_16x16x32_bf16 v[32:35], v[166:169], v[182:185], v[32:35]
	v_mfma_f32_16x16x32_bf16 v[20:23], v[148:151], v[200:203], v[20:23]
	v_mfma_f32_16x16x32_bf16 v[16:19], v[166:169], v[200:203], v[16:19]
	v_mfma_f32_16x16x32_bf16 v[4:7], v[148:151], v[210:213], v[4:7]
	v_mfma_f32_16x16x32_bf16 v[0:3], v[166:169], v[210:213], v[0:3]
	s_setprio 0
	s_barrier
	s_add_u32 s26, s26, 0x8000
	s_addc_u32 s27, s27, 0
	s_add_u32 s6, s6, 0x8000
	s_addc_u32 s7, s7, 0
	s_cmp_ge_i32 s40, s10
	s_mov_b32 s28, s40
	s_cbranch_scc0 .LBB0_145

; #define PG8_STAGE(bufoff, gbase, voff) do { _Pragma("unroll") for (int _i = 0; _i < 2; ++_i) \
;         __builtin_amdgcn_global_load_lds((const unsigned*)((const char*)(gbase) + (voff)[_i]), (PG8_LAS unsigned*)(lds + (bufoff) + ldsw + _i * 8192), 16, 0, 0); } while (0)
; #define PG8_LDA(dst, b, h) do { _Pragma("unroll") for (int m = 0; m < 4; ++m) _Pragma("unroll") for (int k = 0; k < 2; ++k) dst[m][k] = *(const PG8_LAS bf16x8*)(lds + PG8_SA(b, h) + aoff + m * 2048 + k * 1024); } while (0)
; #define PG8_LDB(dst, b, h) do { _Pragma("unroll") for (int n = 0; n < 2; ++n) _Pragma("unroll") for (int k = 0; k < 2; ++k) dst[n][k] = *(const PG8_LAS bf16x8*)(lds + PG8_SB(b, h) + boff + n * 2048 + k * 1024); } while (0)
; #define PG8_MMA(ai, bj, At, Bt) do { __builtin_amdgcn_s_setprio(1); _Pragma("unroll") for (int m = 0; m < 4; ++m) _Pragma("unroll") for (int n = 0; n < 2; ++n) _Pragma("unroll") for (int k = 0; k < 2; ++k) \
;         acc[ai][bj][m][n] = __builtin_amdgcn_mfma_f32_16x16x32_bf16(Bt[n][k], At[m][k], acc[ai][bj][m][n], 0, 0, 0); __builtin_amdgcn_s_setprio(0); } while (0)
; #define PG8_WAIT_V(n) asm volatile("s_waitcnt vmcnt(" #n ")" ::: "memory")
; #define PG8_WAIT_L(n) asm volatile("s_waitcnt lgkmcnt(" #n ")" ::: "memory")
; template <class Epi, class Sched, bool ALIGN_EPI = false, bool SP2 = false>
; __device__ __forceinline__ void gemm_phase(PG8_LAS unsigned char* lds, const Gemm g, const Sched& S, const Epi& E, const int tid_in) {
;     ...
;             const bool last = (t == nt - 2);
;             const char* a1 = cA + (size_t)(t + 1) * kstepA;
;             const char* a2 = last ? nA : cA + (size_t)(t + 2) * kstepA; const char* b2 = last ? nB : cB + (size_t)(t + 2) * kstepB;
;             const char* a3 = a2 + kstepA; const char* b3 = b2 + kstepB;
;             if (last && has_next) S.a_ready(nxt);
;             if constexpr (SP2) {
;             PG8_LDB(B0, 0, 0); PG8_LDB(B1, 0, 1); PG8_SCHED; PG8_LDA(At, 0, 0); PG8_STAGE(PG8_SA(1, 1), a1 + hstepA, voffA);
;             PG8_WAIT_V(8); PG8_WAIT_L(0); PG8_BAR; PG8_MMA(0, 0, At, B0); PG8_MMA(0, 1, At, B1); PG8_BAR; PG8_SCHED;
;             PG8_LDA(At, 0, 1); PG8_STAGE(PG8_SB(0, 0), b2, voffB); PG8_STAGE(PG8_SB(0, 1), b2 + hstepB, voffB); PG8_STAGE(PG8_SA(0, 0), a2, voffA);
;             PG8_WAIT_V(8); PG8_WAIT_L(0); PG8_BAR; PG8_MMA(1, 0, At, B0); PG8_MMA(1, 1, At, B1); PG8_BAR; PG8_SCHED;
.LBB0_232:
	s_andn2_b64 vcc, exec, s[26:27]
	s_cbranch_vccnz .Lzero_acc_3
	s_add_u32 s78, s46, s18
	s_addc_u32 s96, s47, s19
	s_add_u32 s97, s48, 0x8000
	s_addc_u32 s6, s49, 0
	s_mov_b64 s[42:43], 0
	s_add_u32 s4, s42, 1
	s_addc_u32 s5, s43, 0
	s_add_u32 s44, s42, 2
	s_addc_u32 s45, s43, 0
	s_lshl_b64 s[48:49], s[44:45], s70
	s_add_u32 s7, s46, s48
	s_addc_u32 s43, s47, s49
	s_cmp_eq_u32 s52, s42
	s_cselect_b32 vcc_lo, s62, s7
	s_cselect_b32 vcc_hi, s63, s43
	s_cselect_b32 s48, s36, s97
	s_cselect_b32 s49, s37, s6
	s_add_u32 s42, vcc_lo, s91
	s_addc_u32 s43, vcc_hi, 0
	s_add_i32 s7, 0, 0x10000
	s_add_i32 s74, 0, 0x14000
	v_add_u32_e32 v108, s7, v244
	v_add_u32_e32 v156, s74, v244
	ds_read_b128 v[64:67], v108
	ds_read_b128 v[76:79], v108 offset:1024
	ds_read_b128 v[88:91], v108 offset:2048
	ds_read_b128 v[108:111], v108 offset:3072
	ds_read_b128 v[144:147], v156
	ds_read_b128 v[148:151], v156 offset:1024
	ds_read_b128 v[152:155], v156 offset:2048
	ds_read_b128 v[156:159], v156 offset:3072
	s_lshl_b64 s[4:5], s[4:5], s70
	s_add_u32 s4, s78, s4
	s_addc_u32 s5, s96, s5
	v_lshl_add_u64 v[192:193], s[4:5], 0, v[210:211]
	s_add_i32 m0, s13, 0xc000
	ds_read_b128 v[160:163], v248
	ds_read_b128 v[164:167], v248 offset:1024
	ds_read_b128 v[168:171], v248 offset:2048
	ds_read_b128 v[172:175], v248 offset:3072
	ds_read_b128 v[176:179], v248 offset:4096
	ds_read_b128 v[180:183], v248 offset:5120
	ds_read_b128 v[184:187], v248 offset:6144
	ds_read_b128 v[188:191], v248 offset:7168
	global_load_lds_dwordx4 v[192:193], off
	v_lshl_add_u64 v[192:193], s[4:5], 0, v[214:215]
	s_add_i32 m0, s13, 0xe000
	s_nop 0
	global_load_lds_dwordx4 v[192:193], off
	s_waitcnt vmcnt(8)
	s_waitcnt lgkmcnt(0)
	s_barrier
	s_setprio 1
	v_mfma_f32_16x16x32_bf16 v[140:143], v[64:67], v[160:163], 0
	v_mfma_f32_16x16x32_bf16 v[136:139], v[88:91], v[160:163], 0
	v_mfma_f32_16x16x32_bf16 v[124:127], v[64:67], v[168:171], 0
	v_mfma_f32_16x16x32_bf16 v[120:123], v[88:91], v[168:171], 0
	v_mfma_f32_16x16x32_bf16 v[104:107], v[64:67], v[176:179], 0
	v_mfma_f32_16x16x32_bf16 v[100:103], v[88:91], v[176:179], 0
	v_mfma_f32_16x16x32_bf16 v[84:87], v[64:67], v[184:187], 0
	v_mfma_f32_16x16x32_bf16 v[80:83], v[88:91], v[184:187], 0
	v_mfma_f32_16x16x32_bf16 v[140:143], v[76:79], v[164:167], v[140:143]
	v_mfma_f32_16x16x32_bf16 v[136:139], v[108:111], v[164:167], v[136:139]
	v_mfma_f32_16x16x32_bf16 v[124:127], v[76:79], v[172:175], v[124:127]
	v_mfma_f32_16x16x32_bf16 v[120:123], v[108:111], v[172:175], v[120:123]
	v_mfma_f32_16x16x32_bf16 v[104:107], v[76:79], v[180:183], v[104:107]
	v_mfma_f32_16x16x32_bf16 v[100:103], v[108:111], v[180:183], v[100:103]
	v_mfma_f32_16x16x32_bf16 v[84:87], v[76:79], v[188:191], v[84:87]
	v_mfma_f32_16x16x32_bf16 v[80:83], v[108:111], v[188:191], v[80:83]
	s_setprio 0
	s_setprio 1
	v_mfma_f32_16x16x32_bf16 v[132:135], v[144:147], v[160:163], 0
	v_mfma_f32_16x16x32_bf16 v[128:131], v[152:155], v[160:163], 0
	v_mfma_f32_16x16x32_bf16 v[116:119], v[144:147], v[168:171], 0
	v_mfma_f32_16x16x32_bf16 v[112:115], v[152:155], v[168:171], 0
	v_mfma_f32_16x16x32_bf16 v[96:99], v[144:147], v[176:179], 0
	v_mfma_f32_16x16x32_bf16 v[92:95], v[152:155], v[176:179], 0
	v_mfma_f32_16x16x32_bf16 v[72:75], v[144:147], v[184:187], 0
	v_mfma_f32_16x16x32_bf16 v[68:71], v[152:155], v[184:187], 0
	v_mfma_f32_16x16x32_bf16 v[132:135], v[148:151], v[164:167], v[132:135]
	v_mfma_f32_16x16x32_bf16 v[128:131], v[156:159], v[164:167], v[128:131]
	v_mfma_f32_16x16x32_bf16 v[116:119], v[148:151], v[172:175], v[116:119]
	v_mfma_f32_16x16x32_bf16 v[112:115], v[156:159], v[172:175], v[112:115]
	v_mfma_f32_16x16x32_bf16 v[96:99], v[148:151], v[180:183], v[96:99]
	v_mfma_f32_16x16x32_bf16 v[92:95], v[156:159], v[180:183], v[92:95]
	v_mfma_f32_16x16x32_bf16 v[72:75], v[148:151], v[188:191], v[72:75]
	v_mfma_f32_16x16x32_bf16 v[68:71], v[156:159], v[188:191], v[68:71]
	s_setprio 0
	s_barrier
	s_add_i32 s4, s7, s50
	v_lshl_add_u64 v[192:193], s[48:49], 0, v[208:209]
	s_mov_b32 m0, s4
	ds_read_b128 v[160:163], v248 offset:16384
	ds_read_b128 v[164:167], v248 offset:17408
	ds_read_b128 v[168:171], v248 offset:18432
	ds_read_b128 v[172:175], v248 offset:19456
	ds_read_b128 v[176:179], v248 offset:20480
	ds_read_b128 v[180:183], v248 offset:21504
	ds_read_b128 v[184:187], v248 offset:22528
	ds_read_b128 v[188:191], v248 offset:23552
	global_load_lds_dwordx4 v[192:193], off
	s_add_i32 m0, s4, 0x2000
	s_add_u32 s4, s48, s14
	v_lshl_add_u64 v[192:193], s[48:49], 0, v[212:213]
	s_addc_u32 s5, s49, s15
	s_add_i32 s7, s74, s50
	global_load_lds_dwordx4 v[192:193], off
	v_lshl_add_u64 v[192:193], s[4:5], 0, v[208:209]
	s_mov_b32 m0, s7
	s_nop 0
	global_load_lds_dwordx4 v[192:193], off
	v_lshl_add_u64 v[192:193], s[4:5], 0, v[212:213]
	s_add_i32 m0, s7, 0x2000
	s_nop 0
	global_load_lds_dwordx4 v[192:193], off
	v_lshl_add_u64 v[192:193], vcc, 0, v[210:211]
	s_mov_b32 m0, s13
	s_nop 0
	global_load_lds_dwordx4 v[192:193], off
	v_lshl_add_u64 v[192:193], vcc, 0, v[214:215]
	s_mov_b32 m0, s51
	s_nop 0
	global_load_lds_dwordx4 v[192:193], off
	s_waitcnt vmcnt(8)
	s_waitcnt lgkmcnt(0)
	s_barrier
; #define PG8_STAGE(bufoff, gbase, voff) do { _Pragma("unroll") for (int _i = 0; _i < 2; ++_i) \
;         __builtin_amdgcn_global_load_lds((const unsigned*)((const char*)(gbase) + (voff)[_i]), (PG8_LAS unsigned*)(lds + (bufoff) + ldsw + _i * 8192), 16, 0, 0); } while (0)
; #define PG8_LDA(dst, b, h) do { _Pragma("unroll") for (int m = 0; m < 4; ++m) _Pragma("unroll") for (int k = 0; k < 2; ++k) dst[m][k] = *(const PG8_LAS bf16x8*)(lds + PG8_SA(b, h) + aoff + m * 2048 + k * 1024); } while (0)
; #define PG8_LDB(dst, b, h) do { _Pragma("unroll") for (int n = 0; n < 2; ++n) _Pragma("unroll") for (int k = 0; k < 2; ++k) dst[n][k] = *(const PG8_LAS bf16x8*)(lds + PG8_SB(b, h) + boff + n * 2048 + k * 1024); } while (0)
; #define PG8_MMA(ai, bj, At, Bt) do { __builtin_amdgcn_s_setprio(1); _Pragma("unroll") for (int m = 0; m < 4; ++m) _Pragma("unroll") for (int n = 0; n < 2; ++n) _Pragma("unroll") for (int k = 0; k < 2; ++k) \
;         acc[ai][bj][m][n] = __builtin_amdgcn_mfma_f32_16x16x32_bf16(Bt[n][k], At[m][k], acc[ai][bj][m][n], 0, 0, 0); __builtin_amdgcn_s_setprio(0); } while (0)
; #define PG8_WAIT_V(n) asm volatile("s_waitcnt vmcnt(" #n ")" ::: "memory")
; #define PG8_WAIT_L(n) asm volatile("s_waitcnt lgkmcnt(" #n ")" ::: "memory")
; #define PG8_BAR __builtin_amdgcn_s_barrier()
; #define PG8_SCHED __builtin_amdgcn_sched_barrier(0)
; template <class Epi, class Sched, bool ALIGN_EPI = false, bool SP2 = false>
; __device__ __forceinline__ void gemm_phase(PG8_LAS unsigned char* lds, const Gemm g, const Sched& S, const Epi& E, const int tid_in) {
;     ...
;             PG8_WAIT_V(8); PG8_WAIT_L(0); PG8_BAR; PG8_MMA(1, 0, At, B0); PG8_MMA(1, 1, At, B1); PG8_BAR; PG8_SCHED;
;             PG8_LDB(B0, 1, 0); PG8_LDB(B1, 1, 1); PG8_SCHED; PG8_LDA(At, 1, 0); PG8_STAGE(PG8_SA(0, 1), a2 + hstepA, voffA);
;             PG8_WAIT_V(8); PG8_WAIT_L(0); PG8_BAR; PG8_MMA(0, 0, At, B0); PG8_MMA(0, 1, At, B1); PG8_BAR; PG8_SCHED;
	s_setprio 1
	v_mfma_f32_16x16x32_bf16 v[60:63], v[64:67], v[160:163], 0
	v_mfma_f32_16x16x32_bf16 v[56:59], v[88:91], v[160:163], 0
	v_mfma_f32_16x16x32_bf16 v[44:47], v[64:67], v[168:171], 0
	v_mfma_f32_16x16x32_bf16 v[40:43], v[88:91], v[168:171], 0
	v_mfma_f32_16x16x32_bf16 v[28:31], v[64:67], v[176:179], 0
	v_mfma_f32_16x16x32_bf16 v[24:27], v[88:91], v[176:179], 0
	v_mfma_f32_16x16x32_bf16 v[12:15], v[64:67], v[184:187], 0
	v_mfma_f32_16x16x32_bf16 v[8:11], v[88:91], v[184:187], 0
	v_mfma_f32_16x16x32_bf16 v[60:63], v[76:79], v[164:167], v[60:63]
	v_mfma_f32_16x16x32_bf16 v[56:59], v[108:111], v[164:167], v[56:59]
	v_mfma_f32_16x16x32_bf16 v[44:47], v[76:79], v[172:175], v[44:47]
	v_mfma_f32_16x16x32_bf16 v[40:43], v[108:111], v[172:175], v[40:43]
	v_mfma_f32_16x16x32_bf16 v[28:31], v[76:79], v[180:183], v[28:31]
	v_mfma_f32_16x16x32_bf16 v[24:27], v[108:111], v[180:183], v[24:27]
	v_mfma_f32_16x16x32_bf16 v[12:15], v[76:79], v[188:191], v[12:15]
	v_mfma_f32_16x16x32_bf16 v[8:11], v[108:111], v[188:191], v[8:11]
	s_setprio 0
	s_setprio 1
	v_mfma_f32_16x16x32_bf16 v[52:55], v[144:147], v[160:163], 0
	v_mfma_f32_16x16x32_bf16 v[48:51], v[152:155], v[160:163], 0
	v_mfma_f32_16x16x32_bf16 v[36:39], v[144:147], v[168:171], 0
	v_mfma_f32_16x16x32_bf16 v[32:35], v[152:155], v[168:171], 0
	v_mfma_f32_16x16x32_bf16 v[20:23], v[144:147], v[176:179], 0
	v_mfma_f32_16x16x32_bf16 v[16:19], v[152:155], v[176:179], 0
	v_mfma_f32_16x16x32_bf16 v[4:7], v[144:147], v[184:187], 0
	v_mfma_f32_16x16x32_bf16 v[0:3], v[152:155], v[184:187], 0
	v_mfma_f32_16x16x32_bf16 v[52:55], v[148:151], v[164:167], v[52:55]
	v_mfma_f32_16x16x32_bf16 v[48:51], v[156:159], v[164:167], v[48:51]
	v_mfma_f32_16x16x32_bf16 v[36:39], v[148:151], v[172:175], v[36:39]
	v_mfma_f32_16x16x32_bf16 v[32:35], v[156:159], v[172:175], v[32:35]
	v_mfma_f32_16x16x32_bf16 v[20:23], v[148:151], v[180:183], v[20:23]
	v_mfma_f32_16x16x32_bf16 v[16:19], v[156:159], v[180:183], v[16:19]
	v_mfma_f32_16x16x32_bf16 v[4:7], v[148:151], v[188:191], v[4:7]
	v_mfma_f32_16x16x32_bf16 v[0:3], v[156:159], v[188:191], v[0:3]
	s_setprio 0
	s_barrier
	s_add_i32 s7, 0, 0x18000
	s_add_i32 s74, 0, 0x1c000
	v_add_u32_e32 v108, s7, v244
	v_add_u32_e32 v156, s74, v244
	ds_read_b128 v[64:67], v108
	ds_read_b128 v[76:79], v108 offset:1024
	ds_read_b128 v[88:91], v108 offset:2048
	ds_read_b128 v[108:111], v108 offset:3072
	ds_read_b128 v[144:147], v156
	ds_read_b128 v[148:151], v156 offset:1024
	ds_read_b128 v[152:155], v156 offset:2048
	ds_read_b128 v[156:159], v156 offset:3072
	s_add_u32 s4, vcc_lo, s18
	s_addc_u32 s5, vcc_hi, s19
	s_mov_b32 m0, s64
	v_lshl_add_u64 v[192:193], s[4:5], 0, v[210:211]
	ds_read_b128 v[160:163], v248 offset:32768
	ds_read_b128 v[164:167], v248 offset:33792
	ds_read_b128 v[168:171], v248 offset:34816
	ds_read_b128 v[172:175], v248 offset:35840
	ds_read_b128 v[176:179], v248 offset:36864
	ds_read_b128 v[180:183], v248 offset:37888
	ds_read_b128 v[184:187], v248 offset:38912
	ds_read_b128 v[188:191], v248 offset:39936
	global_load_lds_dwordx4 v[192:193], off
	v_lshl_add_u64 v[192:193], s[4:5], 0, v[214:215]
	s_mov_b32 m0, s86
	s_nop 0
	global_load_lds_dwordx4 v[192:193], off
	s_waitcnt vmcnt(8)
	s_waitcnt lgkmcnt(0)
	s_barrier
	s_setprio 1
	v_mfma_f32_16x16x32_bf16 v[140:143], v[64:67], v[160:163], v[140:143]
	v_mfma_f32_16x16x32_bf16 v[136:139], v[88:91], v[160:163], v[136:139]
	v_mfma_f32_16x16x32_bf16 v[124:127], v[64:67], v[168:171], v[124:127]
	v_mfma_f32_16x16x32_bf16 v[120:123], v[88:91], v[168:171], v[120:123]
	v_mfma_f32_16x16x32_bf16 v[104:107], v[64:67], v[176:179], v[104:107]
	v_mfma_f32_16x16x32_bf16 v[100:103], v[88:91], v[176:179], v[100:103]
	v_mfma_f32_16x16x32_bf16 v[84:87], v[64:67], v[184:187], v[84:87]
	v_mfma_f32_16x16x32_bf16 v[80:83], v[88:91], v[184:187], v[80:83]
	v_mfma_f32_16x16x32_bf16 v[140:143], v[76:79], v[164:167], v[140:143]
	v_mfma_f32_16x16x32_bf16 v[136:139], v[108:111], v[164:167], v[136:139]
	v_mfma_f32_16x16x32_bf16 v[124:127], v[76:79], v[172:175], v[124:127]
	v_mfma_f32_16x16x32_bf16 v[120:123], v[108:111], v[172:175], v[120:123]
	v_mfma_f32_16x16x32_bf16 v[104:107], v[76:79], v[180:183], v[104:107]
	v_mfma_f32_16x16x32_bf16 v[100:103], v[108:111], v[180:183], v[100:103]
	v_mfma_f32_16x16x32_bf16 v[84:87], v[76:79], v[188:191], v[84:87]
	v_mfma_f32_16x16x32_bf16 v[80:83], v[108:111], v[188:191], v[80:83]
	s_setprio 0
	s_setprio 1
	v_mfma_f32_16x16x32_bf16 v[132:135], v[144:147], v[160:163], v[132:135]
	v_mfma_f32_16x16x32_bf16 v[128:131], v[152:155], v[160:163], v[128:131]
	v_mfma_f32_16x16x32_bf16 v[116:119], v[144:147], v[168:171], v[116:119]
	v_mfma_f32_16x16x32_bf16 v[112:115], v[152:155], v[168:171], v[112:115]
	v_mfma_f32_16x16x32_bf16 v[96:99], v[144:147], v[176:179], v[96:99]
	v_mfma_f32_16x16x32_bf16 v[92:95], v[152:155], v[176:179], v[92:95]
	v_mfma_f32_16x16x32_bf16 v[72:75], v[144:147], v[184:187], v[72:75]
	v_mfma_f32_16x16x32_bf16 v[68:71], v[152:155], v[184:187], v[68:71]
	v_mfma_f32_16x16x32_bf16 v[132:135], v[148:151], v[164:167], v[132:135]
	v_mfma_f32_16x16x32_bf16 v[128:131], v[156:159], v[164:167], v[128:131]
	v_mfma_f32_16x16x32_bf16 v[116:119], v[148:151], v[172:175], v[116:119]
	v_mfma_f32_16x16x32_bf16 v[112:115], v[156:159], v[172:175], v[112:115]
	v_mfma_f32_16x16x32_bf16 v[96:99], v[148:151], v[180:183], v[96:99]
	v_mfma_f32_16x16x32_bf16 v[92:95], v[156:159], v[180:183], v[92:95]
	v_mfma_f32_16x16x32_bf16 v[72:75], v[148:151], v[188:191], v[72:75]
	v_mfma_f32_16x16x32_bf16 v[68:71], v[156:159], v[188:191], v[68:71]
	s_setprio 0
	s_barrier
; #define PG8_STAGE(bufoff, gbase, voff) do { _Pragma("unroll") for (int _i = 0; _i < 2; ++_i) \
;         __builtin_amdgcn_global_load_lds((const unsigned*)((const char*)(gbase) + (voff)[_i]), (PG8_LAS unsigned*)(lds + (bufoff) + ldsw + _i * 8192), 16, 0, 0); } while (0)
; #define PG8_LDA(dst, b, h) do { _Pragma("unroll") for (int m = 0; m < 4; ++m) _Pragma("unroll") for (int k = 0; k < 2; ++k) dst[m][k] = *(const PG8_LAS bf16x8*)(lds + PG8_SA(b, h) + aoff + m * 2048 + k * 1024); } while (0)
; #define PG8_LDB(dst, b, h) do { _Pragma("unroll") for (int n = 0; n < 2; ++n) _Pragma("unroll") for (int k = 0; k < 2; ++k) dst[n][k] = *(const PG8_LAS bf16x8*)(lds + PG8_SB(b, h) + boff + n * 2048 + k * 1024); } while (0)
; #define PG8_MMA(ai, bj, At, Bt) do { __builtin_amdgcn_s_setprio(1); _Pragma("unroll") for (int m = 0; m < 4; ++m) _Pragma("unroll") for (int n = 0; n < 2; ++n) _Pragma("unroll") for (int k = 0; k < 2; ++k) \
;         acc[ai][bj][m][n] = __builtin_amdgcn_mfma_f32_16x16x32_bf16(Bt[n][k], At[m][k], acc[ai][bj][m][n], 0, 0, 0); __builtin_amdgcn_s_setprio(0); } while (0)
; #define PG8_WAIT_V(n) asm volatile("s_waitcnt vmcnt(" #n ")" ::: "memory")
; #define PG8_BAR __builtin_amdgcn_s_barrier()
; template <class Epi, class Sched, bool ALIGN_EPI = false, bool SP2 = false>
; __device__ __forceinline__ void gemm_phase(PG8_LAS unsigned char* lds, const Gemm g, const Sched& S, const Epi& E, const int tid_in) {
;     ...
;         for (int t = 0; t < nt; t += 2) {
;             const bool last = (t == nt - 2);
;             const char* a1 = cA + (size_t)(t + 1) * kstepA;
;             const char* a2 = last ? nA : cA + (size_t)(t + 2) * kstepA; const char* b2 = last ? nB : cB + (size_t)(t + 2) * kstepB;
;             const char* a3 = a2 + kstepA; const char* b3 = b2 + kstepB;
;             if (last && has_next) S.a_ready(nxt);
;             if constexpr (SP2) {
;             PG8_LDB(B0, 0, 0); PG8_LDB(B1, 0, 1); PG8_SCHED; PG8_LDA(At, 0, 0); PG8_STAGE(PG8_SA(1, 1), a1 + hstepA, voffA);
;             PG8_WAIT_V(8); PG8_WAIT_L(0); PG8_BAR; PG8_MMA(0, 0, At, B0); PG8_MMA(0, 1, At, B1); PG8_BAR; PG8_SCHED;
;     ...
;             PG8_LDA(At, 1, 1); PG8_STAGE(PG8_SB(1, 0), b3, voffB); PG8_STAGE(PG8_SB(1, 1), b3 + hstepB, voffB); PG8_STAGE(PG8_SA(1, 0), a3, voffA);
;             PG8_WAIT_V(8); PG8_WAIT_L(0); PG8_BAR; PG8_MMA(1, 0, At, B0); PG8_MMA(1, 1, At, B1); PG8_BAR; PG8_SCHED;
	s_add_u32 s4, s48, 0x4000
	s_addc_u32 s5, s49, 0
	s_add_i32 s7, s7, s50
	v_lshl_add_u64 v[192:193], s[4:5], 0, v[208:209]
	s_mov_b32 m0, s7
	ds_read_b128 v[160:163], v248 offset:49152
	ds_read_b128 v[164:167], v248 offset:50176
	ds_read_b128 v[168:171], v248 offset:51200
	ds_read_b128 v[172:175], v248 offset:52224
	ds_read_b128 v[176:179], v248 offset:53248
	ds_read_b128 v[180:183], v248 offset:54272
	ds_read_b128 v[184:187], v248 offset:55296
	ds_read_b128 v[188:191], v248 offset:56320
	global_load_lds_dwordx4 v[192:193], off
	s_add_i32 m0, s7, 0x2000
	v_lshl_add_u64 v[192:193], s[4:5], 0, v[212:213]
	s_add_u32 s4, s4, s14
	s_addc_u32 s5, s5, s15
	s_add_i32 s7, s74, s50
	global_load_lds_dwordx4 v[192:193], off
	v_lshl_add_u64 v[192:193], s[4:5], 0, v[208:209]
	s_mov_b32 m0, s7
	s_nop 0
	global_load_lds_dwordx4 v[192:193], off
	v_lshl_add_u64 v[192:193], s[4:5], 0, v[212:213]
	s_add_i32 m0, s7, 0x2000
	s_nop 0
	global_load_lds_dwordx4 v[192:193], off
	v_lshl_add_u64 v[192:193], s[42:43], 0, v[210:211]
	s_mov_b32 m0, s68
	s_nop 0
	global_load_lds_dwordx4 v[192:193], off
	v_lshl_add_u64 v[192:193], s[42:43], 0, v[214:215]
	s_mov_b32 m0, s69
	s_nop 0
	global_load_lds_dwordx4 v[192:193], off
	s_waitcnt vmcnt(8)
	s_waitcnt lgkmcnt(0)
	s_barrier
	s_setprio 1
	v_mfma_f32_16x16x32_bf16 v[60:63], v[64:67], v[160:163], v[60:63]
	v_mfma_f32_16x16x32_bf16 v[56:59], v[88:91], v[160:163], v[56:59]
	v_mfma_f32_16x16x32_bf16 v[44:47], v[64:67], v[168:171], v[44:47]
	v_mfma_f32_16x16x32_bf16 v[40:43], v[88:91], v[168:171], v[40:43]
	v_mfma_f32_16x16x32_bf16 v[28:31], v[64:67], v[176:179], v[28:31]
	v_mfma_f32_16x16x32_bf16 v[24:27], v[88:91], v[176:179], v[24:27]
	v_mfma_f32_16x16x32_bf16 v[12:15], v[64:67], v[184:187], v[12:15]
	v_mfma_f32_16x16x32_bf16 v[8:11], v[88:91], v[184:187], v[8:11]
	v_mfma_f32_16x16x32_bf16 v[60:63], v[76:79], v[164:167], v[60:63]
	v_mfma_f32_16x16x32_bf16 v[56:59], v[108:111], v[164:167], v[56:59]
	v_mfma_f32_16x16x32_bf16 v[44:47], v[76:79], v[172:175], v[44:47]
	v_mfma_f32_16x16x32_bf16 v[40:43], v[108:111], v[172:175], v[40:43]
	v_mfma_f32_16x16x32_bf16 v[28:31], v[76:79], v[180:183], v[28:31]
	v_mfma_f32_16x16x32_bf16 v[24:27], v[108:111], v[180:183], v[24:27]
	v_mfma_f32_16x16x32_bf16 v[12:15], v[76:79], v[188:191], v[12:15]
	v_mfma_f32_16x16x32_bf16 v[8:11], v[108:111], v[188:191], v[8:11]
	s_setprio 0
	s_setprio 1
	v_mfma_f32_16x16x32_bf16 v[52:55], v[144:147], v[160:163], v[52:55]
	v_mfma_f32_16x16x32_bf16 v[48:51], v[152:155], v[160:163], v[48:51]
	v_mfma_f32_16x16x32_bf16 v[36:39], v[144:147], v[168:171], v[36:39]
	v_mfma_f32_16x16x32_bf16 v[32:35], v[152:155], v[168:171], v[32:35]
	v_mfma_f32_16x16x32_bf16 v[20:23], v[144:147], v[176:179], v[20:23]
	v_mfma_f32_16x16x32_bf16 v[16:19], v[152:155], v[176:179], v[16:19]
	v_mfma_f32_16x16x32_bf16 v[4:7], v[144:147], v[184:187], v[4:7]
	v_mfma_f32_16x16x32_bf16 v[0:3], v[152:155], v[184:187], v[0:3]
	v_mfma_f32_16x16x32_bf16 v[52:55], v[148:151], v[164:167], v[52:55]
	v_mfma_f32_16x16x32_bf16 v[48:51], v[156:159], v[164:167], v[48:51]
	v_mfma_f32_16x16x32_bf16 v[36:39], v[148:151], v[172:175], v[36:39]
	v_mfma_f32_16x16x32_bf16 v[32:35], v[156:159], v[172:175], v[32:35]
	v_mfma_f32_16x16x32_bf16 v[20:23], v[148:151], v[180:183], v[20:23]
	v_mfma_f32_16x16x32_bf16 v[16:19], v[156:159], v[180:183], v[16:19]
	v_mfma_f32_16x16x32_bf16 v[4:7], v[148:151], v[188:191], v[4:7]
	v_mfma_f32_16x16x32_bf16 v[0:3], v[156:159], v[188:191], v[0:3]
	s_setprio 0
	s_barrier
	s_add_u32 s97, s97, 0x8000
	s_addc_u32 s6, s6, 0
	s_cmp_ge_i32 s44, s12
	s_mov_b64 s[42:43], s[44:45]
	s_cbranch_scc1 .LBB0_235
.LBB0_234:
	s_add_u32 s4, s42, 1
	s_addc_u32 s5, s43, 0
	s_add_u32 s44, s42, 2
	s_addc_u32 s45, s43, 0
	s_lshl_b64 s[48:49], s[44:45], s70
	s_add_u32 s7, s46, s48
	s_addc_u32 s43, s47, s49
	s_cmp_eq_u32 s52, s42
	s_cselect_b32 vcc_lo, s62, s7
	s_cselect_b32 vcc_hi, s63, s43
	s_cselect_b32 s48, s36, s97
	s_cselect_b32 s49, s37, s6
	s_add_u32 s42, vcc_lo, s91
	s_addc_u32 s43, vcc_hi, 0
	s_add_i32 s7, 0, 0x10000
	s_add_i32 s74, 0, 0x14000
	v_add_u32_e32 v108, s7, v244
	v_add_u32_e32 v156, s74, v244
	ds_read_b128 v[64:67], v108
	ds_read_b128 v[76:79], v108 offset:1024
	ds_read_b128 v[88:91], v108 offset:2048
	ds_read_b128 v[108:111], v108 offset:3072
	ds_read_b128 v[144:147], v156
	ds_read_b128 v[148:151], v156 offset:1024
	ds_read_b128 v[152:155], v156 offset:2048
	ds_read_b128 v[156:159], v156 offset:3072
	s_lshl_b64 s[4:5], s[4:5], s70
	s_add_u32 s4, s78, s4
	s_addc_u32 s5, s96, s5
	v_lshl_add_u64 v[192:193], s[4:5], 0, v[210:211]
	s_add_i32 m0, s13, 0xc000
	ds_read_b128 v[160:163], v248
	ds_read_b128 v[164:167], v248 offset:1024
	ds_read_b128 v[168:171], v248 offset:2048
	ds_read_b128 v[172:175], v248 offset:3072
	ds_read_b128 v[176:179], v248 offset:4096
	ds_read_b128 v[180:183], v248 offset:5120
	ds_read_b128 v[184:187], v248 offset:6144
	ds_read_b128 v[188:191], v248 offset:7168
	global_load_lds_dwordx4 v[192:193], off
	v_lshl_add_u64 v[192:193], s[4:5], 0, v[214:215]
	s_add_i32 m0, s13, 0xe000
	s_nop 0
	global_load_lds_dwordx4 v[192:193], off
	s_waitcnt vmcnt(8)
	s_waitcnt lgkmcnt(0)
	s_barrier
; #define PG8_STAGE(bufoff, gbase, voff) do { _Pragma("unroll") for (int _i = 0; _i < 2; ++_i) \
;         __builtin_amdgcn_global_load_lds((const unsigned*)((const char*)(gbase) + (voff)[_i]), (PG8_LAS unsigned*)(lds + (bufoff) + ldsw + _i * 8192), 16, 0, 0); } while (0)
; #define PG8_LDA(dst, b, h) do { _Pragma("unroll") for (int m = 0; m < 4; ++m) _Pragma("unroll") for (int k = 0; k < 2; ++k) dst[m][k] = *(const PG8_LAS bf16x8*)(lds + PG8_SA(b, h) + aoff + m * 2048 + k * 1024); } while (0)
; #define PG8_MMA(ai, bj, At, Bt) do { __builtin_amdgcn_s_setprio(1); _Pragma("unroll") for (int m = 0; m < 4; ++m) _Pragma("unroll") for (int n = 0; n < 2; ++n) _Pragma("unroll") for (int k = 0; k < 2; ++k) \
;         acc[ai][bj][m][n] = __builtin_amdgcn_mfma_f32_16x16x32_bf16(Bt[n][k], At[m][k], acc[ai][bj][m][n], 0, 0, 0); __builtin_amdgcn_s_setprio(0); } while (0)
; #define PG8_WAIT_V(n) asm volatile("s_waitcnt vmcnt(" #n ")" ::: "memory")
; #define PG8_WAIT_L(n) asm volatile("s_waitcnt lgkmcnt(" #n ")" ::: "memory")
; #define PG8_BAR __builtin_amdgcn_s_barrier()
; #define PG8_SCHED __builtin_amdgcn_sched_barrier(0)
; template <class Epi, class Sched, bool ALIGN_EPI = false, bool SP2 = false>
; __device__ __forceinline__ void gemm_phase(PG8_LAS unsigned char* lds, const Gemm g, const Sched& S, const Epi& E, const int tid_in) {
;     ...
;             PG8_WAIT_V(8); PG8_WAIT_L(0); PG8_BAR; PG8_MMA(0, 0, At, B0); PG8_MMA(0, 1, At, B1); PG8_BAR; PG8_SCHED;
;             PG8_LDA(At, 0, 1); PG8_STAGE(PG8_SB(0, 0), b2, voffB); PG8_STAGE(PG8_SB(0, 1), b2 + hstepB, voffB); PG8_STAGE(PG8_SA(0, 0), a2, voffA);
;             PG8_WAIT_V(8); PG8_WAIT_L(0); PG8_BAR; PG8_MMA(1, 0, At, B0); PG8_MMA(1, 1, At, B1); PG8_BAR; PG8_SCHED;
	s_setprio 1
	v_mfma_f32_16x16x32_bf16 v[140:143], v[64:67], v[160:163], v[140:143]
	v_mfma_f32_16x16x32_bf16 v[136:139], v[88:91], v[160:163], v[136:139]
	v_mfma_f32_16x16x32_bf16 v[124:127], v[64:67], v[168:171], v[124:127]
	v_mfma_f32_16x16x32_bf16 v[120:123], v[88:91], v[168:171], v[120:123]
	v_mfma_f32_16x16x32_bf16 v[104:107], v[64:67], v[176:179], v[104:107]
	v_mfma_f32_16x16x32_bf16 v[100:103], v[88:91], v[176:179], v[100:103]
	v_mfma_f32_16x16x32_bf16 v[84:87], v[64:67], v[184:187], v[84:87]
	v_mfma_f32_16x16x32_bf16 v[80:83], v[88:91], v[184:187], v[80:83]
	v_mfma_f32_16x16x32_bf16 v[140:143], v[76:79], v[164:167], v[140:143]
	v_mfma_f32_16x16x32_bf16 v[136:139], v[108:111], v[164:167], v[136:139]
	v_mfma_f32_16x16x32_bf16 v[124:127], v[76:79], v[172:175], v[124:127]
	v_mfma_f32_16x16x32_bf16 v[120:123], v[108:111], v[172:175], v[120:123]
	v_mfma_f32_16x16x32_bf16 v[104:107], v[76:79], v[180:183], v[104:107]
	v_mfma_f32_16x16x32_bf16 v[100:103], v[108:111], v[180:183], v[100:103]
	v_mfma_f32_16x16x32_bf16 v[84:87], v[76:79], v[188:191], v[84:87]
	v_mfma_f32_16x16x32_bf16 v[80:83], v[108:111], v[188:191], v[80:83]
	s_setprio 0
	s_setprio 1
	v_mfma_f32_16x16x32_bf16 v[132:135], v[144:147], v[160:163], v[132:135]
	v_mfma_f32_16x16x32_bf16 v[128:131], v[152:155], v[160:163], v[128:131]
	v_mfma_f32_16x16x32_bf16 v[116:119], v[144:147], v[168:171], v[116:119]
	v_mfma_f32_16x16x32_bf16 v[112:115], v[152:155], v[168:171], v[112:115]
	v_mfma_f32_16x16x32_bf16 v[96:99], v[144:147], v[176:179], v[96:99]
	v_mfma_f32_16x16x32_bf16 v[92:95], v[152:155], v[176:179], v[92:95]
	v_mfma_f32_16x16x32_bf16 v[72:75], v[144:147], v[184:187], v[72:75]
	v_mfma_f32_16x16x32_bf16 v[68:71], v[152:155], v[184:187], v[68:71]
	v_mfma_f32_16x16x32_bf16 v[132:135], v[148:151], v[164:167], v[132:135]
	v_mfma_f32_16x16x32_bf16 v[128:131], v[156:159], v[164:167], v[128:131]
	v_mfma_f32_16x16x32_bf16 v[116:119], v[148:151], v[172:175], v[116:119]
	v_mfma_f32_16x16x32_bf16 v[112:115], v[156:159], v[172:175], v[112:115]
	v_mfma_f32_16x16x32_bf16 v[96:99], v[148:151], v[180:183], v[96:99]
	v_mfma_f32_16x16x32_bf16 v[92:95], v[156:159], v[180:183], v[92:95]
	v_mfma_f32_16x16x32_bf16 v[72:75], v[148:151], v[188:191], v[72:75]
	v_mfma_f32_16x16x32_bf16 v[68:71], v[156:159], v[188:191], v[68:71]
	s_setprio 0
	s_barrier
	s_add_i32 s4, s7, s50
	v_lshl_add_u64 v[192:193], s[48:49], 0, v[208:209]
	s_mov_b32 m0, s4
	ds_read_b128 v[160:163], v248 offset:16384
	ds_read_b128 v[164:167], v248 offset:17408
	ds_read_b128 v[168:171], v248 offset:18432
	ds_read_b128 v[172:175], v248 offset:19456
	ds_read_b128 v[176:179], v248 offset:20480
	ds_read_b128 v[180:183], v248 offset:21504
	ds_read_b128 v[184:187], v248 offset:22528
	ds_read_b128 v[188:191], v248 offset:23552
	global_load_lds_dwordx4 v[192:193], off
	s_add_i32 m0, s4, 0x2000
	s_add_u32 s4, s48, s14
	v_lshl_add_u64 v[192:193], s[48:49], 0, v[212:213]
	s_addc_u32 s5, s49, s15
	s_add_i32 s7, s74, s50
	global_load_lds_dwordx4 v[192:193], off
	v_lshl_add_u64 v[192:193], s[4:5], 0, v[208:209]
	s_mov_b32 m0, s7
	s_nop 0
	global_load_lds_dwordx4 v[192:193], off
	v_lshl_add_u64 v[192:193], s[4:5], 0, v[212:213]
	s_add_i32 m0, s7, 0x2000
	s_nop 0
	global_load_lds_dwordx4 v[192:193], off
	v_lshl_add_u64 v[192:193], vcc, 0, v[210:211]
	s_mov_b32 m0, s13
	s_nop 0
	global_load_lds_dwordx4 v[192:193], off
	v_lshl_add_u64 v[192:193], vcc, 0, v[214:215]
	s_mov_b32 m0, s51
	s_nop 0
	global_load_lds_dwordx4 v[192:193], off
	s_waitcnt vmcnt(8)
	s_waitcnt lgkmcnt(0)
	s_barrier
	s_setprio 1
	v_mfma_f32_16x16x32_bf16 v[60:63], v[64:67], v[160:163], v[60:63]
	v_mfma_f32_16x16x32_bf16 v[56:59], v[88:91], v[160:163], v[56:59]
	v_mfma_f32_16x16x32_bf16 v[44:47], v[64:67], v[168:171], v[44:47]
	v_mfma_f32_16x16x32_bf16 v[40:43], v[88:91], v[168:171], v[40:43]
	v_mfma_f32_16x16x32_bf16 v[28:31], v[64:67], v[176:179], v[28:31]
	v_mfma_f32_16x16x32_bf16 v[24:27], v[88:91], v[176:179], v[24:27]
	v_mfma_f32_16x16x32_bf16 v[12:15], v[64:67], v[184:187], v[12:15]
	v_mfma_f32_16x16x32_bf16 v[8:11], v[88:91], v[184:187], v[8:11]
	v_mfma_f32_16x16x32_bf16 v[60:63], v[76:79], v[164:167], v[60:63]
	v_mfma_f32_16x16x32_bf16 v[56:59], v[108:111], v[164:167], v[56:59]
	v_mfma_f32_16x16x32_bf16 v[44:47], v[76:79], v[172:175], v[44:47]
	v_mfma_f32_16x16x32_bf16 v[40:43], v[108:111], v[172:175], v[40:43]
	v_mfma_f32_16x16x32_bf16 v[28:31], v[76:79], v[180:183], v[28:31]
	v_mfma_f32_16x16x32_bf16 v[24:27], v[108:111], v[180:183], v[24:27]
	v_mfma_f32_16x16x32_bf16 v[12:15], v[76:79], v[188:191], v[12:15]
	v_mfma_f32_16x16x32_bf16 v[8:11], v[108:111], v[188:191], v[8:11]
	s_setprio 0
	s_setprio 1
	v_mfma_f32_16x16x32_bf16 v[52:55], v[144:147], v[160:163], v[52:55]
	v_mfma_f32_16x16x32_bf16 v[48:51], v[152:155], v[160:163], v[48:51]
	v_mfma_f32_16x16x32_bf16 v[36:39], v[144:147], v[168:171], v[36:39]
	v_mfma_f32_16x16x32_bf16 v[32:35], v[152:155], v[168:171], v[32:35]
	v_mfma_f32_16x16x32_bf16 v[20:23], v[144:147], v[176:179], v[20:23]
	v_mfma_f32_16x16x32_bf16 v[16:19], v[152:155], v[176:179], v[16:19]
	v_mfma_f32_16x16x32_bf16 v[4:7], v[144:147], v[184:187], v[4:7]
	v_mfma_f32_16x16x32_bf16 v[0:3], v[152:155], v[184:187], v[0:3]
	v_mfma_f32_16x16x32_bf16 v[52:55], v[148:151], v[164:167], v[52:55]
	v_mfma_f32_16x16x32_bf16 v[48:51], v[156:159], v[164:167], v[48:51]
	v_mfma_f32_16x16x32_bf16 v[36:39], v[148:151], v[172:175], v[36:39]
	v_mfma_f32_16x16x32_bf16 v[32:35], v[156:159], v[172:175], v[32:35]
	v_mfma_f32_16x16x32_bf16 v[20:23], v[148:151], v[180:183], v[20:23]
	v_mfma_f32_16x16x32_bf16 v[16:19], v[156:159], v[180:183], v[16:19]
	v_mfma_f32_16x16x32_bf16 v[4:7], v[148:151], v[188:191], v[4:7]
	v_mfma_f32_16x16x32_bf16 v[0:3], v[156:159], v[188:191], v[0:3]
	s_setprio 0
	s_barrier
; #define PG8_STAGE(bufoff, gbase, voff) do { _Pragma("unroll") for (int _i = 0; _i < 2; ++_i) \
;         __builtin_amdgcn_global_load_lds((const unsigned*)((const char*)(gbase) + (voff)[_i]), (PG8_LAS unsigned*)(lds + (bufoff) + ldsw + _i * 8192), 16, 0, 0); } while (0)
; #define PG8_LDA(dst, b, h) do { _Pragma("unroll") for (int m = 0; m < 4; ++m) _Pragma("unroll") for (int k = 0; k < 2; ++k) dst[m][k] = *(const PG8_LAS bf16x8*)(lds + PG8_SA(b, h) + aoff + m * 2048 + k * 1024); } while (0)
; #define PG8_LDB(dst, b, h) do { _Pragma("unroll") for (int n = 0; n < 2; ++n) _Pragma("unroll") for (int k = 0; k < 2; ++k) dst[n][k] = *(const PG8_LAS bf16x8*)(lds + PG8_SB(b, h) + boff + n * 2048 + k * 1024); } while (0)
; #define PG8_MMA(ai, bj, At, Bt) do { __builtin_amdgcn_s_setprio(1); _Pragma("unroll") for (int m = 0; m < 4; ++m) _Pragma("unroll") for (int n = 0; n < 2; ++n) _Pragma("unroll") for (int k = 0; k < 2; ++k) \
;         acc[ai][bj][m][n] = __builtin_amdgcn_mfma_f32_16x16x32_bf16(Bt[n][k], At[m][k], acc[ai][bj][m][n], 0, 0, 0); __builtin_amdgcn_s_setprio(0); } while (0)
; #define PG8_WAIT_V(n) asm volatile("s_waitcnt vmcnt(" #n ")" ::: "memory")
; #define PG8_WAIT_L(n) asm volatile("s_waitcnt lgkmcnt(" #n ")" ::: "memory")
; #define PG8_BAR __builtin_amdgcn_s_barrier()
; #define PG8_SCHED __builtin_amdgcn_sched_barrier(0)
; template <class Epi, class Sched, bool ALIGN_EPI = false, bool SP2 = false>
; __device__ __forceinline__ void gemm_phase(PG8_LAS unsigned char* lds, const Gemm g, const Sched& S, const Epi& E, const int tid_in) {
;     ...
;             PG8_LDB(B0, 1, 0); PG8_LDB(B1, 1, 1); PG8_SCHED; PG8_LDA(At, 1, 0); PG8_STAGE(PG8_SA(0, 1), a2 + hstepA, voffA);
;             PG8_WAIT_V(8); PG8_WAIT_L(0); PG8_BAR; PG8_MMA(0, 0, At, B0); PG8_MMA(0, 1, At, B1); PG8_BAR; PG8_SCHED;
	s_add_i32 s7, 0, 0x18000
	s_add_i32 s74, 0, 0x1c000
	v_add_u32_e32 v108, s7, v244
	v_add_u32_e32 v156, s74, v244
	ds_read_b128 v[64:67], v108
	ds_read_b128 v[76:79], v108 offset:1024
	ds_read_b128 v[88:91], v108 offset:2048
	ds_read_b128 v[108:111], v108 offset:3072
	ds_read_b128 v[144:147], v156
	ds_read_b128 v[148:151], v156 offset:1024
	ds_read_b128 v[152:155], v156 offset:2048
	ds_read_b128 v[156:159], v156 offset:3072
	s_add_u32 s4, vcc_lo, s18
	s_addc_u32 s5, vcc_hi, s19
	s_mov_b32 m0, s64
	v_lshl_add_u64 v[192:193], s[4:5], 0, v[210:211]
	ds_read_b128 v[160:163], v248 offset:32768
	ds_read_b128 v[164:167], v248 offset:33792
	ds_read_b128 v[168:171], v248 offset:34816
	ds_read_b128 v[172:175], v248 offset:35840
	ds_read_b128 v[176:179], v248 offset:36864
	ds_read_b128 v[180:183], v248 offset:37888
	ds_read_b128 v[184:187], v248 offset:38912
	ds_read_b128 v[188:191], v248 offset:39936
	global_load_lds_dwordx4 v[192:193], off
	v_lshl_add_u64 v[192:193], s[4:5], 0, v[214:215]
	s_mov_b32 m0, s86
	s_nop 0
	global_load_lds_dwordx4 v[192:193], off
	s_waitcnt vmcnt(8)
	s_waitcnt lgkmcnt(0)
	s_barrier
	s_setprio 1
	v_mfma_f32_16x16x32_bf16 v[140:143], v[64:67], v[160:163], v[140:143]
	v_mfma_f32_16x16x32_bf16 v[136:139], v[88:91], v[160:163], v[136:139]
	v_mfma_f32_16x16x32_bf16 v[124:127], v[64:67], v[168:171], v[124:127]
	v_mfma_f32_16x16x32_bf16 v[120:123], v[88:91], v[168:171], v[120:123]
	v_mfma_f32_16x16x32_bf16 v[104:107], v[64:67], v[176:179], v[104:107]
	v_mfma_f32_16x16x32_bf16 v[100:103], v[88:91], v[176:179], v[100:103]
	v_mfma_f32_16x16x32_bf16 v[84:87], v[64:67], v[184:187], v[84:87]
	v_mfma_f32_16x16x32_bf16 v[80:83], v[88:91], v[184:187], v[80:83]
	v_mfma_f32_16x16x32_bf16 v[140:143], v[76:79], v[164:167], v[140:143]
	v_mfma_f32_16x16x32_bf16 v[136:139], v[108:111], v[164:167], v[136:139]
	v_mfma_f32_16x16x32_bf16 v[124:127], v[76:79], v[172:175], v[124:127]
	v_mfma_f32_16x16x32_bf16 v[120:123], v[108:111], v[172:175], v[120:123]
	v_mfma_f32_16x16x32_bf16 v[104:107], v[76:79], v[180:183], v[104:107]
	v_mfma_f32_16x16x32_bf16 v[100:103], v[108:111], v[180:183], v[100:103]
	v_mfma_f32_16x16x32_bf16 v[84:87], v[76:79], v[188:191], v[84:87]
	v_mfma_f32_16x16x32_bf16 v[80:83], v[108:111], v[188:191], v[80:83]
	s_setprio 0
	s_setprio 1
	v_mfma_f32_16x16x32_bf16 v[132:135], v[144:147], v[160:163], v[132:135]
	v_mfma_f32_16x16x32_bf16 v[128:131], v[152:155], v[160:163], v[128:131]
	v_mfma_f32_16x16x32_bf16 v[116:119], v[144:147], v[168:171], v[116:119]
	v_mfma_f32_16x16x32_bf16 v[112:115], v[152:155], v[168:171], v[112:115]
	v_mfma_f32_16x16x32_bf16 v[96:99], v[144:147], v[176:179], v[96:99]
	v_mfma_f32_16x16x32_bf16 v[92:95], v[152:155], v[176:179], v[92:95]
	v_mfma_f32_16x16x32_bf16 v[72:75], v[144:147], v[184:187], v[72:75]
	v_mfma_f32_16x16x32_bf16 v[68:71], v[152:155], v[184:187], v[68:71]
	v_mfma_f32_16x16x32_bf16 v[132:135], v[148:151], v[164:167], v[132:135]
	v_mfma_f32_16x16x32_bf16 v[128:131], v[156:159], v[164:167], v[128:131]
	v_mfma_f32_16x16x32_bf16 v[116:119], v[148:151], v[172:175], v[116:119]
	v_mfma_f32_16x16x32_bf16 v[112:115], v[156:159], v[172:175], v[112:115]
	v_mfma_f32_16x16x32_bf16 v[96:99], v[148:151], v[180:183], v[96:99]
	v_mfma_f32_16x16x32_bf16 v[92:95], v[156:159], v[180:183], v[92:95]
	v_mfma_f32_16x16x32_bf16 v[72:75], v[148:151], v[188:191], v[72:75]
	v_mfma_f32_16x16x32_bf16 v[68:71], v[156:159], v[188:191], v[68:71]
	s_setprio 0
	s_barrier
; #define PG8_STAGE(bufoff, gbase, voff) do { _Pragma("unroll") for (int _i = 0; _i < 2; ++_i) \
;         __builtin_amdgcn_global_load_lds((const unsigned*)((const char*)(gbase) + (voff)[_i]), (PG8_LAS unsigned*)(lds + (bufoff) + ldsw + _i * 8192), 16, 0, 0); } while (0)
; #define PG8_LDA(dst, b, h) do { _Pragma("unroll") for (int m = 0; m < 4; ++m) _Pragma("unroll") for (int k = 0; k < 2; ++k) dst[m][k] = *(const PG8_LAS bf16x8*)(lds + PG8_SA(b, h) + aoff + m * 2048 + k * 1024); } while (0)
; #define PG8_MMA(ai, bj, At, Bt) do { __builtin_amdgcn_s_setprio(1); _Pragma("unroll") for (int m = 0; m < 4; ++m) _Pragma("unroll") for (int n = 0; n < 2; ++n) _Pragma("unroll") for (int k = 0; k < 2; ++k) \
;         acc[ai][bj][m][n] = __builtin_amdgcn_mfma_f32_16x16x32_bf16(Bt[n][k], At[m][k], acc[ai][bj][m][n], 0, 0, 0); __builtin_amdgcn_s_setprio(0); } while (0)
; #define PG8_WAIT_V(n) asm volatile("s_waitcnt vmcnt(" #n ")" ::: "memory")
; #define PG8_WAIT_L(n) asm volatile("s_waitcnt lgkmcnt(" #n ")" ::: "memory")
; #define PG8_BAR __builtin_amdgcn_s_barrier()
; #define PG8_SCHED __builtin_amdgcn_sched_barrier(0)
; template <class Epi, class Sched, bool ALIGN_EPI = false, bool SP2 = false>
; __device__ __forceinline__ void gemm_phase(PG8_LAS unsigned char* lds, const Gemm g, const Sched& S, const Epi& E, const int tid_in) {
;     ...
;         for (int t = 0; t < nt; t += 2) {
;     ...
;             PG8_LDA(At, 1, 1); PG8_STAGE(PG8_SB(1, 0), b3, voffB); PG8_STAGE(PG8_SB(1, 1), b3 + hstepB, voffB); PG8_STAGE(PG8_SA(1, 0), a3, voffA);
;             PG8_WAIT_V(8); PG8_WAIT_L(0); PG8_BAR; PG8_MMA(1, 0, At, B0); PG8_MMA(1, 1, At, B1); PG8_BAR; PG8_SCHED;
	s_add_u32 s4, s48, 0x4000
	s_addc_u32 s5, s49, 0
	s_add_i32 s7, s7, s50
	v_lshl_add_u64 v[192:193], s[4:5], 0, v[208:209]
	s_mov_b32 m0, s7
	ds_read_b128 v[160:163], v248 offset:49152
	ds_read_b128 v[164:167], v248 offset:50176
	ds_read_b128 v[168:171], v248 offset:51200
	ds_read_b128 v[172:175], v248 offset:52224
	ds_read_b128 v[176:179], v248 offset:53248
	ds_read_b128 v[180:183], v248 offset:54272
	ds_read_b128 v[184:187], v248 offset:55296
	ds_read_b128 v[188:191], v248 offset:56320
	global_load_lds_dwordx4 v[192:193], off
	s_add_i32 m0, s7, 0x2000
	v_lshl_add_u64 v[192:193], s[4:5], 0, v[212:213]
	s_add_u32 s4, s4, s14
	s_addc_u32 s5, s5, s15
	s_add_i32 s7, s74, s50
	global_load_lds_dwordx4 v[192:193], off
	v_lshl_add_u64 v[192:193], s[4:5], 0, v[208:209]
	s_mov_b32 m0, s7
	s_nop 0
	global_load_lds_dwordx4 v[192:193], off
	v_lshl_add_u64 v[192:193], s[4:5], 0, v[212:213]
	s_add_i32 m0, s7, 0x2000
	s_nop 0
	global_load_lds_dwordx4 v[192:193], off
	v_lshl_add_u64 v[192:193], s[42:43], 0, v[210:211]
	s_mov_b32 m0, s68
	s_nop 0
	global_load_lds_dwordx4 v[192:193], off
	v_lshl_add_u64 v[192:193], s[42:43], 0, v[214:215]
	s_mov_b32 m0, s69
	s_nop 0
	global_load_lds_dwordx4 v[192:193], off
	s_waitcnt vmcnt(8)
	s_waitcnt lgkmcnt(0)
	s_barrier
	s_setprio 1
	v_mfma_f32_16x16x32_bf16 v[60:63], v[64:67], v[160:163], v[60:63]
	v_mfma_f32_16x16x32_bf16 v[56:59], v[88:91], v[160:163], v[56:59]
	v_mfma_f32_16x16x32_bf16 v[44:47], v[64:67], v[168:171], v[44:47]
	v_mfma_f32_16x16x32_bf16 v[40:43], v[88:91], v[168:171], v[40:43]
	v_mfma_f32_16x16x32_bf16 v[28:31], v[64:67], v[176:179], v[28:31]
	v_mfma_f32_16x16x32_bf16 v[24:27], v[88:91], v[176:179], v[24:27]
	v_mfma_f32_16x16x32_bf16 v[12:15], v[64:67], v[184:187], v[12:15]
	v_mfma_f32_16x16x32_bf16 v[8:11], v[88:91], v[184:187], v[8:11]
	v_mfma_f32_16x16x32_bf16 v[60:63], v[76:79], v[164:167], v[60:63]
	v_mfma_f32_16x16x32_bf16 v[56:59], v[108:111], v[164:167], v[56:59]
	v_mfma_f32_16x16x32_bf16 v[44:47], v[76:79], v[172:175], v[44:47]
	v_mfma_f32_16x16x32_bf16 v[40:43], v[108:111], v[172:175], v[40:43]
	v_mfma_f32_16x16x32_bf16 v[28:31], v[76:79], v[180:183], v[28:31]
	v_mfma_f32_16x16x32_bf16 v[24:27], v[108:111], v[180:183], v[24:27]
	v_mfma_f32_16x16x32_bf16 v[12:15], v[76:79], v[188:191], v[12:15]
	v_mfma_f32_16x16x32_bf16 v[8:11], v[108:111], v[188:191], v[8:11]
	s_setprio 0
	s_setprio 1
	v_mfma_f32_16x16x32_bf16 v[52:55], v[144:147], v[160:163], v[52:55]
	v_mfma_f32_16x16x32_bf16 v[48:51], v[152:155], v[160:163], v[48:51]
	v_mfma_f32_16x16x32_bf16 v[36:39], v[144:147], v[168:171], v[36:39]
	v_mfma_f32_16x16x32_bf16 v[32:35], v[152:155], v[168:171], v[32:35]
	v_mfma_f32_16x16x32_bf16 v[20:23], v[144:147], v[176:179], v[20:23]
	v_mfma_f32_16x16x32_bf16 v[16:19], v[152:155], v[176:179], v[16:19]
	v_mfma_f32_16x16x32_bf16 v[4:7], v[144:147], v[184:187], v[4:7]
	v_mfma_f32_16x16x32_bf16 v[0:3], v[152:155], v[184:187], v[0:3]
	v_mfma_f32_16x16x32_bf16 v[52:55], v[148:151], v[164:167], v[52:55]
	v_mfma_f32_16x16x32_bf16 v[48:51], v[156:159], v[164:167], v[48:51]
	v_mfma_f32_16x16x32_bf16 v[36:39], v[148:151], v[172:175], v[36:39]
	v_mfma_f32_16x16x32_bf16 v[32:35], v[156:159], v[172:175], v[32:35]
	v_mfma_f32_16x16x32_bf16 v[20:23], v[148:151], v[180:183], v[20:23]
	v_mfma_f32_16x16x32_bf16 v[16:19], v[156:159], v[180:183], v[16:19]
	v_mfma_f32_16x16x32_bf16 v[4:7], v[148:151], v[188:191], v[4:7]
	v_mfma_f32_16x16x32_bf16 v[0:3], v[156:159], v[188:191], v[0:3]
	s_setprio 0
	s_barrier
	s_add_u32 s97, s97, 0x8000
	s_addc_u32 s6, s6, 0
	s_cmp_ge_i32 s44, s12
	s_mov_b64 s[42:43], s[44:45]
	s_cbranch_scc0 .LBB0_234
